# P4 gate loads issued lane-permuted (4 lanes = 64 contiguous bytes) and routed back with ds_bpermute, on top of batched epilogue loads
# speedup vs baseline: 1.0218x; 1.0081x over previous
; #define GAS __attribute__((address_space(1)))
; __device__ __forceinline__ unsigned cvt_pk_bf16(float lo, float hi) { f32x2 v = {lo, hi}; bf16x2_t b = __builtin_convertvector(v, bf16x2_t); return __builtin_bit_cast(unsigned, b); }
; __device__ __forceinline__ float bf_lo(unsigned u) { return __uint_as_float(u << 16); }
; __device__ __forceinline__ float bf_hi(unsigned u) { return __uint_as_float(u & 0xffff0000u); }
;     __device__ __forceinline__ void operator()(f32x4 (&acc)[2][2][4][2], const Unit& u, int wr, int wc, int fr, int fq) const {
;         const int br = u.pm >> 7, pm = u.pm & 127, pn = u.pn & 3;
;         const int row0 = pm * BM + wr * 64 + fr; const int col0 = pn * BM + wc * 32 + 8 * fq;
; #pragma unroll
;         for (int ai = 0; ai < 2; ++ai)
; #pragma unroll
;             for (int m = 0; m < 4; ++m) { const int row = row0 + ai * HALF + m * 16; const GAS bf16_t* gp = ((br < 2) ? g01 + (size_t)br * MROWS * 1024 : g2) + (size_t)row * 1024 + col0; const GAS bf16_t* gn = ((br == 0) ? g01 + (size_t)MROWS * 1024 : g2) + (size_t)row * 1024 + col0; GAS bf16_t* mp = Mg + (size_t)row * 1024 + col0;
; #pragma unroll
;                 for (int bj = 0; bj < 2; ++bj) { const u32x4 g = *(const GAS u32x4*)(gp + bj * HALF);
;                     f32x4 s0 = {bf_lo(g.x), bf_hi(g.x), bf_lo(g.y), bf_hi(g.y)}, s1 = {bf_lo(g.z), bf_hi(g.z), bf_lo(g.w), bf_hi(g.w)};
;                     if (br < 2) { const u32x4 h = *(const GAS u32x4*)(gn + bj * HALF);
;                         const f32x4 d0 = {bf_lo(h.x), bf_hi(h.x), bf_lo(h.y), bf_hi(h.y)}, d1 = {bf_lo(h.z), bf_hi(h.z), bf_lo(h.w), bf_hi(h.w)};
; #pragma unroll
;                         for (int e = 0; e < 4; ++e) { s0[e] *= __builtin_amdgcn_rcpf(fmaxf(d0[e], 1e-30f)); s1[e] *= __builtin_amdgcn_rcpf(fmaxf(d1[e], 1e-30f)); }
;                         acc[ai][bj][m][0] *= s0; acc[ai][bj][m][1] *= s1;
;                     } else { const f32x4 v0 = acc[ai][bj][m][0] * s0, v1 = acc[ai][bj][m][1] * s1;
;                         u32x4 w; w.x = cvt_pk_bf16(v0[0], v0[1]); w.y = cvt_pk_bf16(v0[2], v0[3]); w.z = cvt_pk_bf16(v1[0], v1[1]); w.w = cvt_pk_bf16(v1[2], v1[3]);
;                         *(GAS u32x4*)(mp + bj * HALF) = w; } } }
.LBB0_517:
	s_lshl_b32 s7, s8, 8
	s_and_b32 s7, s7, 0x7f00
	v_add_u32_e32 v2, s7, v158
	s_lshl_b32 s7, s24, 8
	s_ashr_i32 s6, s8, 7
	s_and_b32 s7, s7, 0x300
	s_cmp_gt_i32 s6, 1
	v_or_b32_e32 v0, s7, v160
	s_cselect_b64 s[24:25], -1, 0
	s_ashr_i32 s7, s6, 31
	s_lshl_b64 s[20:21], s[6:7], 26
	s_add_u32 s7, s29, s20
	s_addc_u32 s11, s28, s21
	s_cmp_lt_i32 s6, 2
	v_ashrrev_i32_e32 v3, 31, v2
	s_cselect_b32 s22, s7, s39
	s_cselect_b32 s23, s11, s40
	v_lshlrev_b64 v[148:149], 11, v[2:3]
	v_lshl_add_u64 v[144:145], s[22:23], 0, v[148:149]
	v_lshlrev_b32_e32 v0, 1, v0
	v_lshl_add_u64 v[146:147], v[144:145], 0, v[0:1]
	v_lshl_add_u64 v[144:145], s[2:3], 0, v[148:149]
	s_cmpk_lt_u32 s8, 0x80
	s_mov_b64 s[6:7], -1
	v_lshl_add_u64 v[144:145], v[144:145], 0, v[0:1]
	s_cselect_b32 s21, s44, s40
	s_cselect_b32 s20, s43, s39
	s_and_b64 vcc, exec, s[24:25]
	v_and_b32_e32 v245, 63, v166
	v_lshrrev_b32_e32 v246, 2, v245
	v_and_b32_e32 v247, 15, v245
	v_sub_u32_e32 v246, v246, v247
	v_and_b32_e32 v199, 3, v245
	v_lshrrev_b32_e32 v244, 4, v245
	v_sub_u32_e32 v199, v199, v244
	v_lshlrev_b32_e32 v199, 4, v199
	v_lshl_add_u32 v246, v246, 11, v199
	v_lshlrev_b32_e32 v247, 2, v247
	v_add_lshl_u32 v244, v247, v244, 2
	v_lshlrev_b32_e32 v198, 11, v2
	v_add3_u32 v198, v198, v0, v246
	global_load_dwordx4 v[200:203], v198, s[22:23]
	global_load_dwordx4 v[204:207], v198, s[20:21]
	global_load_dwordx4 v[208:211], v198, s[22:23] offset:256
	global_load_dwordx4 v[212:215], v198, s[20:21] offset:256
	v_add_u32_e32 v199, 0x8000, v198
	global_load_dwordx4 v[216:219], v199, s[22:23]
	global_load_dwordx4 v[220:223], v199, s[20:21]
	global_load_dwordx4 v[224:227], v199, s[22:23] offset:256
	global_load_dwordx4 v[228:231], v199, s[20:21] offset:256
	s_waitcnt vmcnt(0)
	s_nop 1
	ds_bpermute_b32 v162, v244, v200
	ds_bpermute_b32 v163, v244, v201
	ds_bpermute_b32 v164, v244, v202
	ds_bpermute_b32 v165, v244, v203
	s_waitcnt lgkmcnt(0)
	v_lshlrev_b32_e32 v156, 16, v162
	v_and_b32_e32 v157, 0xffff0000, v162
	v_lshlrev_b32_e32 v152, 16, v163
	v_and_b32_e32 v153, 0xffff0000, v163
	v_lshlrev_b32_e32 v154, 16, v164
	v_and_b32_e32 v155, 0xffff0000, v164
	v_lshlrev_b32_e32 v150, 16, v165
	v_and_b32_e32 v151, 0xffff0000, v165
	s_cbranch_vccz .LBB0_519
	v_pk_mul_f32 v[164:165], v[130:131], v[152:153]
	v_pk_mul_f32 v[162:163], v[128:129], v[156:157]
	v_pk_mul_f32 v[192:193], v[126:127], v[150:151]
	v_pk_mul_f32 v[194:195], v[124:125], v[154:155]
	v_cvt_pk_bf16_f32 v162, v162, v163
	v_cvt_pk_bf16_f32 v163, v164, v165
	v_cvt_pk_bf16_f32 v164, v194, v195
	v_cvt_pk_bf16_f32 v165, v192, v193
	global_store_dwordx4 v[144:145], v[162:165], off
	s_mov_b64 s[6:7], 0
.LBB0_519:
	v_lshl_add_u64 v[148:149], s[20:21], 0, v[148:149]
	s_andn2_b64 vcc, exec, s[6:7]
	v_lshl_add_u64 v[148:149], v[148:149], 0, v[0:1]
	s_cbranch_vccnz .LBB0_521
	s_nop 1
	ds_bpermute_b32 v162, v244, v204
	ds_bpermute_b32 v163, v244, v205
	ds_bpermute_b32 v164, v244, v206
	ds_bpermute_b32 v165, v244, v207
	s_waitcnt lgkmcnt(0)
	v_lshlrev_b32_e32 v193, 16, v163
	v_and_b32_e32 v194, 0xffff0000, v163
	v_lshlrev_b32_e32 v163, 16, v164
	v_max_f32_e32 v163, v163, v163
	v_lshlrev_b32_e32 v182, 16, v162
	v_and_b32_e32 v192, 0xffff0000, v162
	v_max_f32_e32 v163, 0xda24260, v163
	v_and_b32_e32 v195, 0xffff0000, v164
	v_max_f32_e32 v162, v182, v182
	v_rcp_f32_e32 v164, v163
	v_max_f32_e32 v163, v192, v192
	v_max_f32_e32 v162, 0xda24260, v162
	v_max_f32_e32 v163, 0xda24260, v163
	v_rcp_f32_e32 v162, v162
	v_rcp_f32_e32 v163, v163
	v_lshlrev_b32_e32 v196, 16, v165
	v_and_b32_e32 v197, 0xffff0000, v165
	v_pk_mul_f32 v[156:157], v[162:163], v[156:157]
	v_max_f32_e32 v162, v195, v195
	v_max_f32_e32 v162, 0xda24260, v162
	v_rcp_f32_e32 v165, v162
	v_max_f32_e32 v163, v196, v196
	v_max_f32_e32 v163, 0xda24260, v163
	v_max_f32_e32 v162, v193, v193
	v_pk_mul_f32 v[154:155], v[164:165], v[154:155]
	v_rcp_f32_e32 v164, v163
	v_max_f32_e32 v163, v194, v194
	v_max_f32_e32 v162, 0xda24260, v162
	v_max_f32_e32 v163, 0xda24260, v163
	v_rcp_f32_e32 v162, v162
	v_rcp_f32_e32 v163, v163
	v_pk_mul_f32 v[128:129], v[128:129], v[156:157]
	v_pk_mul_f32 v[124:125], v[124:125], v[154:155]
	v_pk_mul_f32 v[152:153], v[162:163], v[152:153]
	v_max_f32_e32 v162, v197, v197
	v_max_f32_e32 v162, 0xda24260, v162
	v_rcp_f32_e32 v165, v162
	v_pk_mul_f32 v[130:131], v[130:131], v[152:153]
	v_pk_mul_f32 v[150:151], v[164:165], v[150:151]
	s_nop 0
	v_pk_mul_f32 v[126:127], v[126:127], v[150:151]
.LBB0_521:
	v_cndmask_b32_e64 v146, 0, 1, s[24:25]
	v_cmp_ne_u32_e64 s[6:7], 1, v146
	s_andn2_b64 vcc, exec, s[24:25]
	s_mov_b64 s[24:25], -1
	s_nop 1
	ds_bpermute_b32 v162, v244, v208
	ds_bpermute_b32 v163, v244, v209
	ds_bpermute_b32 v164, v244, v210
	ds_bpermute_b32 v165, v244, v211
	s_waitcnt lgkmcnt(0)
	v_lshlrev_b32_e32 v154, 16, v162
	v_and_b32_e32 v155, 0xffff0000, v162
	v_lshlrev_b32_e32 v150, 16, v163
	v_and_b32_e32 v151, 0xffff0000, v163
	v_lshlrev_b32_e32 v152, 16, v164
	v_and_b32_e32 v153, 0xffff0000, v164
	v_lshlrev_b32_e32 v146, 16, v165
	v_and_b32_e32 v147, 0xffff0000, v165
	s_cbranch_vccnz .LBB0_523
	v_pk_mul_f32 v[156:157], v[98:99], v[150:151]
	v_pk_mul_f32 v[162:163], v[96:97], v[154:155]
	v_pk_mul_f32 v[192:193], v[94:95], v[146:147]
	v_pk_mul_f32 v[164:165], v[92:93], v[152:153]
	v_cvt_pk_bf16_f32 v162, v162, v163
	v_cvt_pk_bf16_f32 v163, v156, v157
	v_cvt_pk_bf16_f32 v164, v164, v165
	v_cvt_pk_bf16_f32 v165, v192, v193
	s_mov_b64 s[24:25], 0
	global_store_dwordx4 v[144:145], v[162:165], off offset:256
; #define GAS __attribute__((address_space(1)))
; __device__ __forceinline__ unsigned cvt_pk_bf16(float lo, float hi) { f32x2 v = {lo, hi}; bf16x2_t b = __builtin_convertvector(v, bf16x2_t); return __builtin_bit_cast(unsigned, b); }
; __device__ __forceinline__ float bf_lo(unsigned u) { return __uint_as_float(u << 16); }
; __device__ __forceinline__ float bf_hi(unsigned u) { return __uint_as_float(u & 0xffff0000u); }
;     __device__ __forceinline__ void operator()(f32x4 (&acc)[2][2][4][2], const Unit& u, int wr, int wc, int fr, int fq) const {
;         const int br = u.pm >> 7, pm = u.pm & 127, pn = u.pn & 3;
;         const int row0 = pm * BM + wr * 64 + fr; const int col0 = pn * BM + wc * 32 + 8 * fq;
; #pragma unroll
;         for (int ai = 0; ai < 2; ++ai)
; #pragma unroll
;             for (int m = 0; m < 4; ++m) { const int row = row0 + ai * HALF + m * 16; const GAS bf16_t* gp = ((br < 2) ? g01 + (size_t)br * MROWS * 1024 : g2) + (size_t)row * 1024 + col0; const GAS bf16_t* gn = ((br == 0) ? g01 + (size_t)MROWS * 1024 : g2) + (size_t)row * 1024 + col0; GAS bf16_t* mp = Mg + (size_t)row * 1024 + col0;
; #pragma unroll
;                 for (int bj = 0; bj < 2; ++bj) { const u32x4 g = *(const GAS u32x4*)(gp + bj * HALF);
;                     f32x4 s0 = {bf_lo(g.x), bf_hi(g.x), bf_lo(g.y), bf_hi(g.y)}, s1 = {bf_lo(g.z), bf_hi(g.z), bf_lo(g.w), bf_hi(g.w)};
;                     if (br < 2) { const u32x4 h = *(const GAS u32x4*)(gn + bj * HALF);
;                         const f32x4 d0 = {bf_lo(h.x), bf_hi(h.x), bf_lo(h.y), bf_hi(h.y)}, d1 = {bf_lo(h.z), bf_hi(h.z), bf_lo(h.w), bf_hi(h.w)};
; #pragma unroll
;                         for (int e = 0; e < 4; ++e) { s0[e] *= __builtin_amdgcn_rcpf(fmaxf(d0[e], 1e-30f)); s1[e] *= __builtin_amdgcn_rcpf(fmaxf(d1[e], 1e-30f)); }
;                         acc[ai][bj][m][0] *= s0; acc[ai][bj][m][1] *= s1;
;                     } else { const f32x4 v0 = acc[ai][bj][m][0] * s0, v1 = acc[ai][bj][m][1] * s1;
;                         u32x4 w; w.x = cvt_pk_bf16(v0[0], v0[1]); w.y = cvt_pk_bf16(v0[2], v0[3]); w.z = cvt_pk_bf16(v1[0], v1[1]); w.w = cvt_pk_bf16(v1[2], v1[3]);
;                         *(GAS u32x4*)(mp + bj * HALF) = w; } } }
.LBB0_523:
	s_andn2_b64 vcc, exec, s[24:25]
	s_cbranch_vccnz .LBB0_525
	s_nop 1
	ds_bpermute_b32 v162, v244, v212
	ds_bpermute_b32 v163, v244, v213
	ds_bpermute_b32 v164, v244, v214
	ds_bpermute_b32 v165, v244, v215
	s_waitcnt lgkmcnt(0)
	v_lshlrev_b32_e32 v148, 16, v164
	v_and_b32_e32 v149, 0xffff0000, v164
	v_max_f32_e32 v148, v148, v148
	v_max_f32_e32 v149, v149, v149
	v_lshlrev_b32_e32 v144, 16, v162
	v_and_b32_e32 v145, 0xffff0000, v162
	v_max_f32_e32 v148, 0xda24260, v148
	v_max_f32_e32 v149, 0xda24260, v149
	v_max_f32_e32 v144, v144, v144
	v_rcp_f32_e32 v148, v148
	v_max_f32_e32 v145, v145, v145
	v_rcp_f32_e32 v149, v149
	v_max_f32_e32 v144, 0xda24260, v144
	v_max_f32_e32 v145, 0xda24260, v145
	v_rcp_f32_e32 v144, v144
	v_rcp_f32_e32 v145, v145
	v_lshlrev_b32_e32 v162, 16, v165
	v_pk_mul_f32 v[148:149], v[148:149], v[152:153]
	v_max_f32_e32 v153, v162, v162
	v_lshlrev_b32_e32 v156, 16, v163
	v_and_b32_e32 v157, 0xffff0000, v163
	v_max_f32_e32 v153, 0xda24260, v153
	v_pk_mul_f32 v[144:145], v[144:145], v[154:155]
	v_max_f32_e32 v152, v156, v156
	v_rcp_f32_e32 v154, v153
	v_max_f32_e32 v153, v157, v157
	v_max_f32_e32 v152, 0xda24260, v152
	v_max_f32_e32 v153, 0xda24260, v153
	v_rcp_f32_e32 v152, v152
	v_rcp_f32_e32 v153, v153
	v_and_b32_e32 v163, 0xffff0000, v165
	v_pk_mul_f32 v[96:97], v[96:97], v[144:145]
	v_pk_mul_f32 v[92:93], v[92:93], v[148:149]
	v_pk_mul_f32 v[150:151], v[152:153], v[150:151]
	v_max_f32_e32 v152, v163, v163
	v_max_f32_e32 v152, 0xda24260, v152
	v_rcp_f32_e32 v155, v152
	v_pk_mul_f32 v[98:99], v[98:99], v[150:151]
	v_pk_mul_f32 v[146:147], v[154:155], v[146:147]
	s_nop 0
	v_pk_mul_f32 v[94:95], v[94:95], v[146:147]
.LBB0_525:
	v_or_b32_e32 v144, 16, v2
	v_ashrrev_i32_e32 v145, 31, v144
	v_lshlrev_b64 v[148:149], 11, v[144:145]
	v_lshl_add_u64 v[144:145], s[22:23], 0, v[148:149]
	v_lshl_add_u64 v[146:147], v[144:145], 0, v[0:1]
	v_lshl_add_u64 v[144:145], s[2:3], 0, v[148:149]
	s_and_b64 vcc, exec, s[6:7]
	v_lshl_add_u64 v[144:145], v[144:145], 0, v[0:1]
	s_mov_b64 s[24:25], -1
	s_nop 1
	ds_bpermute_b32 v162, v244, v216
	ds_bpermute_b32 v163, v244, v217
	ds_bpermute_b32 v164, v244, v218
	ds_bpermute_b32 v165, v244, v219
	s_waitcnt lgkmcnt(0)
	v_lshlrev_b32_e32 v156, 16, v162
	v_and_b32_e32 v157, 0xffff0000, v162
	v_lshlrev_b32_e32 v152, 16, v163
	v_and_b32_e32 v153, 0xffff0000, v163
	v_lshlrev_b32_e32 v154, 16, v164
	v_and_b32_e32 v155, 0xffff0000, v164
	v_lshlrev_b32_e32 v150, 16, v165
	v_and_b32_e32 v151, 0xffff0000, v165
	s_cbranch_vccnz .LBB0_527
	v_pk_mul_f32 v[164:165], v[122:123], v[152:153]
	v_pk_mul_f32 v[162:163], v[120:121], v[156:157]
	v_pk_mul_f32 v[192:193], v[118:119], v[150:151]
	v_pk_mul_f32 v[194:195], v[116:117], v[154:155]
	v_cvt_pk_bf16_f32 v162, v162, v163
	v_cvt_pk_bf16_f32 v163, v164, v165
	v_cvt_pk_bf16_f32 v164, v194, v195
	v_cvt_pk_bf16_f32 v165, v192, v193
	s_mov_b64 s[24:25], 0
	global_store_dwordx4 v[144:145], v[162:165], off
.LBB0_527:
	v_lshl_add_u64 v[148:149], s[20:21], 0, v[148:149]
	s_andn2_b64 vcc, exec, s[24:25]
	v_lshl_add_u64 v[148:149], v[148:149], 0, v[0:1]
	s_cbranch_vccnz .LBB0_529
	s_nop 1
	ds_bpermute_b32 v162, v244, v220
	ds_bpermute_b32 v163, v244, v221
	ds_bpermute_b32 v164, v244, v222
	ds_bpermute_b32 v165, v244, v223
	s_waitcnt lgkmcnt(0)
	v_lshlrev_b32_e32 v193, 16, v163
	v_and_b32_e32 v194, 0xffff0000, v163
	v_lshlrev_b32_e32 v163, 16, v164
	v_max_f32_e32 v163, v163, v163
	v_lshlrev_b32_e32 v182, 16, v162
	v_and_b32_e32 v192, 0xffff0000, v162
	v_max_f32_e32 v163, 0xda24260, v163
	v_and_b32_e32 v195, 0xffff0000, v164
	v_max_f32_e32 v162, v182, v182
	v_rcp_f32_e32 v164, v163
	v_max_f32_e32 v163, v192, v192
	v_max_f32_e32 v162, 0xda24260, v162
	v_max_f32_e32 v163, 0xda24260, v163
	v_rcp_f32_e32 v162, v162
	v_rcp_f32_e32 v163, v163
	v_lshlrev_b32_e32 v196, 16, v165
	v_and_b32_e32 v197, 0xffff0000, v165
	v_pk_mul_f32 v[156:157], v[162:163], v[156:157]
	v_max_f32_e32 v162, v195, v195
	v_max_f32_e32 v162, 0xda24260, v162
	v_rcp_f32_e32 v165, v162
	v_max_f32_e32 v163, v196, v196
	v_max_f32_e32 v163, 0xda24260, v163
	v_max_f32_e32 v162, v193, v193
	v_pk_mul_f32 v[154:155], v[164:165], v[154:155]
	v_rcp_f32_e32 v164, v163
	v_max_f32_e32 v163, v194, v194
	v_max_f32_e32 v162, 0xda24260, v162
	v_max_f32_e32 v163, 0xda24260, v163
	v_rcp_f32_e32 v162, v162
	v_rcp_f32_e32 v163, v163
	v_pk_mul_f32 v[120:121], v[120:121], v[156:157]
	v_pk_mul_f32 v[116:117], v[116:117], v[154:155]
	v_pk_mul_f32 v[152:153], v[162:163], v[152:153]
	v_max_f32_e32 v162, v197, v197
	v_max_f32_e32 v162, 0xda24260, v162
	v_rcp_f32_e32 v165, v162
	v_pk_mul_f32 v[122:123], v[122:123], v[152:153]
	v_pk_mul_f32 v[150:151], v[164:165], v[150:151]
	s_nop 0
	v_pk_mul_f32 v[118:119], v[118:119], v[150:151]
.LBB0_529:
	s_and_b64 vcc, exec, s[6:7]
	s_mov_b64 s[24:25], -1
	s_nop 1
	ds_bpermute_b32 v162, v244, v224
	ds_bpermute_b32 v163, v244, v225
	ds_bpermute_b32 v164, v244, v226
	ds_bpermute_b32 v165, v244, v227
	s_waitcnt lgkmcnt(0)
	v_lshlrev_b32_e32 v154, 16, v162
	v_and_b32_e32 v155, 0xffff0000, v162
	v_lshlrev_b32_e32 v150, 16, v163
	v_and_b32_e32 v151, 0xffff0000, v163
	v_lshlrev_b32_e32 v152, 16, v164
	v_and_b32_e32 v153, 0xffff0000, v164
	v_lshlrev_b32_e32 v146, 16, v165
	v_and_b32_e32 v147, 0xffff0000, v165
	s_cbranch_vccnz .LBB0_531
	v_pk_mul_f32 v[156:157], v[90:91], v[150:151]
	v_pk_mul_f32 v[162:163], v[88:89], v[154:155]
	v_pk_mul_f32 v[192:193], v[86:87], v[146:147]
	v_pk_mul_f32 v[164:165], v[84:85], v[152:153]
	v_cvt_pk_bf16_f32 v162, v162, v163
	v_cvt_pk_bf16_f32 v163, v156, v157
	v_cvt_pk_bf16_f32 v164, v164, v165
	v_cvt_pk_bf16_f32 v165, v192, v193
	s_mov_b64 s[24:25], 0
	global_store_dwordx4 v[144:145], v[162:165], off offset:256
; #define GAS __attribute__((address_space(1)))
; __device__ __forceinline__ unsigned cvt_pk_bf16(float lo, float hi) { f32x2 v = {lo, hi}; bf16x2_t b = __builtin_convertvector(v, bf16x2_t); return __builtin_bit_cast(unsigned, b); }
; __device__ __forceinline__ float bf_lo(unsigned u) { return __uint_as_float(u << 16); }
; __device__ __forceinline__ float bf_hi(unsigned u) { return __uint_as_float(u & 0xffff0000u); }
;     __device__ __forceinline__ void operator()(f32x4 (&acc)[2][2][4][2], const Unit& u, int wr, int wc, int fr, int fq) const {
;         const int br = u.pm >> 7, pm = u.pm & 127, pn = u.pn & 3;
;         const int row0 = pm * BM + wr * 64 + fr; const int col0 = pn * BM + wc * 32 + 8 * fq;
; #pragma unroll
;         for (int ai = 0; ai < 2; ++ai)
; #pragma unroll
;             for (int m = 0; m < 4; ++m) { const int row = row0 + ai * HALF + m * 16; const GAS bf16_t* gp = ((br < 2) ? g01 + (size_t)br * MROWS * 1024 : g2) + (size_t)row * 1024 + col0; const GAS bf16_t* gn = ((br == 0) ? g01 + (size_t)MROWS * 1024 : g2) + (size_t)row * 1024 + col0; GAS bf16_t* mp = Mg + (size_t)row * 1024 + col0;
; #pragma unroll
;                 for (int bj = 0; bj < 2; ++bj) { const u32x4 g = *(const GAS u32x4*)(gp + bj * HALF);
;                     f32x4 s0 = {bf_lo(g.x), bf_hi(g.x), bf_lo(g.y), bf_hi(g.y)}, s1 = {bf_lo(g.z), bf_hi(g.z), bf_lo(g.w), bf_hi(g.w)};
;                     if (br < 2) { const u32x4 h = *(const GAS u32x4*)(gn + bj * HALF);
;                         const f32x4 d0 = {bf_lo(h.x), bf_hi(h.x), bf_lo(h.y), bf_hi(h.y)}, d1 = {bf_lo(h.z), bf_hi(h.z), bf_lo(h.w), bf_hi(h.w)};
; #pragma unroll
;                         for (int e = 0; e < 4; ++e) { s0[e] *= __builtin_amdgcn_rcpf(fmaxf(d0[e], 1e-30f)); s1[e] *= __builtin_amdgcn_rcpf(fmaxf(d1[e], 1e-30f)); }
;                         acc[ai][bj][m][0] *= s0; acc[ai][bj][m][1] *= s1;
;                     } else { const f32x4 v0 = acc[ai][bj][m][0] * s0, v1 = acc[ai][bj][m][1] * s1;
;                         u32x4 w; w.x = cvt_pk_bf16(v0[0], v0[1]); w.y = cvt_pk_bf16(v0[2], v0[3]); w.z = cvt_pk_bf16(v1[0], v1[1]); w.w = cvt_pk_bf16(v1[2], v1[3]);
;                         *(GAS u32x4*)(mp + bj * HALF) = w; } } }
.LBB0_531:
	s_andn2_b64 vcc, exec, s[24:25]
	s_cbranch_vccnz .LBB0_533
	s_nop 1
	ds_bpermute_b32 v162, v244, v228
	ds_bpermute_b32 v163, v244, v229
	ds_bpermute_b32 v164, v244, v230
	ds_bpermute_b32 v165, v244, v231
	s_waitcnt lgkmcnt(0)
	v_lshlrev_b32_e32 v148, 16, v164
	v_and_b32_e32 v149, 0xffff0000, v164
	v_max_f32_e32 v148, v148, v148
	v_max_f32_e32 v149, v149, v149
	v_lshlrev_b32_e32 v144, 16, v162
	v_and_b32_e32 v145, 0xffff0000, v162
	v_max_f32_e32 v148, 0xda24260, v148
	v_max_f32_e32 v149, 0xda24260, v149
	v_max_f32_e32 v144, v144, v144
	v_rcp_f32_e32 v148, v148
	v_max_f32_e32 v145, v145, v145
	v_rcp_f32_e32 v149, v149
	v_max_f32_e32 v144, 0xda24260, v144
	v_max_f32_e32 v145, 0xda24260, v145
	v_rcp_f32_e32 v144, v144
	v_rcp_f32_e32 v145, v145
	v_lshlrev_b32_e32 v162, 16, v165
	v_pk_mul_f32 v[148:149], v[148:149], v[152:153]
	v_max_f32_e32 v153, v162, v162
	v_lshlrev_b32_e32 v156, 16, v163
	v_and_b32_e32 v157, 0xffff0000, v163
	v_max_f32_e32 v153, 0xda24260, v153
	v_pk_mul_f32 v[144:145], v[144:145], v[154:155]
	v_max_f32_e32 v152, v156, v156
	v_rcp_f32_e32 v154, v153
	v_max_f32_e32 v153, v157, v157
	v_max_f32_e32 v152, 0xda24260, v152
	v_max_f32_e32 v153, 0xda24260, v153
	v_rcp_f32_e32 v152, v152
	v_rcp_f32_e32 v153, v153
	v_and_b32_e32 v163, 0xffff0000, v165
	v_pk_mul_f32 v[88:89], v[88:89], v[144:145]
	v_pk_mul_f32 v[84:85], v[84:85], v[148:149]
	v_pk_mul_f32 v[150:151], v[152:153], v[150:151]
	v_max_f32_e32 v152, v163, v163
	v_max_f32_e32 v152, 0xda24260, v152
	v_rcp_f32_e32 v155, v152
	v_pk_mul_f32 v[90:91], v[90:91], v[150:151]
	v_pk_mul_f32 v[146:147], v[154:155], v[146:147]
	s_nop 0
	v_pk_mul_f32 v[86:87], v[86:87], v[146:147]
.LBB0_533:
	v_or_b32_e32 v144, 32, v2
	v_ashrrev_i32_e32 v145, 31, v144
	v_lshlrev_b64 v[148:149], 11, v[144:145]
	v_lshl_add_u64 v[144:145], s[22:23], 0, v[148:149]
	v_lshl_add_u64 v[146:147], v[144:145], 0, v[0:1]
	v_lshl_add_u64 v[144:145], s[2:3], 0, v[148:149]
	s_and_b64 vcc, exec, s[6:7]
	v_lshl_add_u64 v[144:145], v[144:145], 0, v[0:1]
	s_mov_b64 s[24:25], -1
	v_add_u32_e32 v199, 0x10000, v198
	global_load_dwordx4 v[200:203], v199, s[22:23]
	global_load_dwordx4 v[204:207], v199, s[20:21]
	global_load_dwordx4 v[208:211], v199, s[22:23] offset:256
	global_load_dwordx4 v[212:215], v199, s[20:21] offset:256
	v_add_u32_e32 v199, 0x18000, v198
	global_load_dwordx4 v[216:219], v199, s[22:23]
	global_load_dwordx4 v[220:223], v199, s[20:21]
	global_load_dwordx4 v[224:227], v199, s[22:23] offset:256
	global_load_dwordx4 v[228:231], v199, s[20:21] offset:256
	s_waitcnt vmcnt(0)
	s_nop 1
	ds_bpermute_b32 v162, v244, v200
	ds_bpermute_b32 v163, v244, v201
	ds_bpermute_b32 v164, v244, v202
	ds_bpermute_b32 v165, v244, v203
	s_waitcnt lgkmcnt(0)
	v_lshlrev_b32_e32 v156, 16, v162
	v_and_b32_e32 v157, 0xffff0000, v162
	v_lshlrev_b32_e32 v152, 16, v163
	v_and_b32_e32 v153, 0xffff0000, v163
	v_lshlrev_b32_e32 v154, 16, v164
	v_and_b32_e32 v155, 0xffff0000, v164
	v_lshlrev_b32_e32 v150, 16, v165
	v_and_b32_e32 v151, 0xffff0000, v165
	s_cbranch_vccnz .LBB0_535
	v_pk_mul_f32 v[164:165], v[114:115], v[152:153]
	v_pk_mul_f32 v[162:163], v[112:113], v[156:157]
	v_pk_mul_f32 v[192:193], v[110:111], v[150:151]
	v_pk_mul_f32 v[194:195], v[108:109], v[154:155]
	v_cvt_pk_bf16_f32 v162, v162, v163
	v_cvt_pk_bf16_f32 v163, v164, v165
	v_cvt_pk_bf16_f32 v164, v194, v195
	v_cvt_pk_bf16_f32 v165, v192, v193
	s_mov_b64 s[24:25], 0
	global_store_dwordx4 v[144:145], v[162:165], off
.LBB0_535:
	v_lshl_add_u64 v[148:149], s[20:21], 0, v[148:149]
	s_andn2_b64 vcc, exec, s[24:25]
	v_lshl_add_u64 v[148:149], v[148:149], 0, v[0:1]
	s_cbranch_vccnz .LBB0_537
	s_nop 1
	ds_bpermute_b32 v162, v244, v204
	ds_bpermute_b32 v163, v244, v205
	ds_bpermute_b32 v164, v244, v206
	ds_bpermute_b32 v165, v244, v207
	s_waitcnt lgkmcnt(0)
	v_lshlrev_b32_e32 v193, 16, v163
	v_and_b32_e32 v194, 0xffff0000, v163
	v_lshlrev_b32_e32 v163, 16, v164
	v_max_f32_e32 v163, v163, v163
	v_lshlrev_b32_e32 v182, 16, v162
	v_and_b32_e32 v192, 0xffff0000, v162
	v_max_f32_e32 v163, 0xda24260, v163
	v_and_b32_e32 v195, 0xffff0000, v164
	v_max_f32_e32 v162, v182, v182
	v_rcp_f32_e32 v164, v163
	v_max_f32_e32 v163, v192, v192
	v_max_f32_e32 v162, 0xda24260, v162
	v_max_f32_e32 v163, 0xda24260, v163
	v_rcp_f32_e32 v162, v162
	v_rcp_f32_e32 v163, v163
	v_lshlrev_b32_e32 v196, 16, v165
	v_and_b32_e32 v197, 0xffff0000, v165
	v_pk_mul_f32 v[156:157], v[162:163], v[156:157]
	v_max_f32_e32 v162, v195, v195
	v_max_f32_e32 v162, 0xda24260, v162
	v_rcp_f32_e32 v165, v162
	v_max_f32_e32 v163, v196, v196
	v_max_f32_e32 v163, 0xda24260, v163
	v_max_f32_e32 v162, v193, v193
	v_pk_mul_f32 v[154:155], v[164:165], v[154:155]
	v_rcp_f32_e32 v164, v163
	v_max_f32_e32 v163, v194, v194
	v_max_f32_e32 v162, 0xda24260, v162
	v_max_f32_e32 v163, 0xda24260, v163
	v_rcp_f32_e32 v162, v162
	v_rcp_f32_e32 v163, v163
	v_pk_mul_f32 v[112:113], v[112:113], v[156:157]
	v_pk_mul_f32 v[108:109], v[108:109], v[154:155]
	v_pk_mul_f32 v[152:153], v[162:163], v[152:153]
	v_max_f32_e32 v162, v197, v197
	v_max_f32_e32 v162, 0xda24260, v162
	v_rcp_f32_e32 v165, v162
	v_pk_mul_f32 v[114:115], v[114:115], v[152:153]
	v_pk_mul_f32 v[150:151], v[164:165], v[150:151]
	s_nop 0
	v_pk_mul_f32 v[110:111], v[110:111], v[150:151]
; #define GAS __attribute__((address_space(1)))
; __device__ __forceinline__ unsigned cvt_pk_bf16(float lo, float hi) { f32x2 v = {lo, hi}; bf16x2_t b = __builtin_convertvector(v, bf16x2_t); return __builtin_bit_cast(unsigned, b); }
; __device__ __forceinline__ float bf_lo(unsigned u) { return __uint_as_float(u << 16); }
; __device__ __forceinline__ float bf_hi(unsigned u) { return __uint_as_float(u & 0xffff0000u); }
;     __device__ __forceinline__ void operator()(f32x4 (&acc)[2][2][4][2], const Unit& u, int wr, int wc, int fr, int fq) const {
;         const int br = u.pm >> 7, pm = u.pm & 127, pn = u.pn & 3;
;         const int row0 = pm * BM + wr * 64 + fr; const int col0 = pn * BM + wc * 32 + 8 * fq;
; #pragma unroll
;         for (int ai = 0; ai < 2; ++ai)
; #pragma unroll
;             for (int m = 0; m < 4; ++m) { const int row = row0 + ai * HALF + m * 16; const GAS bf16_t* gp = ((br < 2) ? g01 + (size_t)br * MROWS * 1024 : g2) + (size_t)row * 1024 + col0; const GAS bf16_t* gn = ((br == 0) ? g01 + (size_t)MROWS * 1024 : g2) + (size_t)row * 1024 + col0; GAS bf16_t* mp = Mg + (size_t)row * 1024 + col0;
; #pragma unroll
;                 for (int bj = 0; bj < 2; ++bj) { const u32x4 g = *(const GAS u32x4*)(gp + bj * HALF);
;                     f32x4 s0 = {bf_lo(g.x), bf_hi(g.x), bf_lo(g.y), bf_hi(g.y)}, s1 = {bf_lo(g.z), bf_hi(g.z), bf_lo(g.w), bf_hi(g.w)};
;                     if (br < 2) { const u32x4 h = *(const GAS u32x4*)(gn + bj * HALF);
;                         const f32x4 d0 = {bf_lo(h.x), bf_hi(h.x), bf_lo(h.y), bf_hi(h.y)}, d1 = {bf_lo(h.z), bf_hi(h.z), bf_lo(h.w), bf_hi(h.w)};
; #pragma unroll
;                         for (int e = 0; e < 4; ++e) { s0[e] *= __builtin_amdgcn_rcpf(fmaxf(d0[e], 1e-30f)); s1[e] *= __builtin_amdgcn_rcpf(fmaxf(d1[e], 1e-30f)); }
;                         acc[ai][bj][m][0] *= s0; acc[ai][bj][m][1] *= s1;
;                     } else { const f32x4 v0 = acc[ai][bj][m][0] * s0, v1 = acc[ai][bj][m][1] * s1;
;                         u32x4 w; w.x = cvt_pk_bf16(v0[0], v0[1]); w.y = cvt_pk_bf16(v0[2], v0[3]); w.z = cvt_pk_bf16(v1[0], v1[1]); w.w = cvt_pk_bf16(v1[2], v1[3]);
;                         *(GAS u32x4*)(mp + bj * HALF) = w; } } }
.LBB0_537:
	s_and_b64 vcc, exec, s[6:7]
	s_mov_b64 s[24:25], -1
	s_nop 1
	ds_bpermute_b32 v162, v244, v208
	ds_bpermute_b32 v163, v244, v209
	ds_bpermute_b32 v164, v244, v210
	ds_bpermute_b32 v165, v244, v211
	s_waitcnt lgkmcnt(0)
	v_lshlrev_b32_e32 v154, 16, v162
	v_and_b32_e32 v155, 0xffff0000, v162
	v_lshlrev_b32_e32 v150, 16, v163
	v_and_b32_e32 v151, 0xffff0000, v163
	v_lshlrev_b32_e32 v152, 16, v164
	v_and_b32_e32 v153, 0xffff0000, v164
	v_lshlrev_b32_e32 v146, 16, v165
	v_and_b32_e32 v147, 0xffff0000, v165
	s_cbranch_vccnz .LBB0_539
	v_pk_mul_f32 v[156:157], v[82:83], v[150:151]
	v_pk_mul_f32 v[162:163], v[80:81], v[154:155]
	v_pk_mul_f32 v[192:193], v[78:79], v[146:147]
	v_pk_mul_f32 v[164:165], v[76:77], v[152:153]
	v_cvt_pk_bf16_f32 v162, v162, v163
	v_cvt_pk_bf16_f32 v163, v156, v157
	v_cvt_pk_bf16_f32 v164, v164, v165
	v_cvt_pk_bf16_f32 v165, v192, v193
	s_mov_b64 s[24:25], 0
	global_store_dwordx4 v[144:145], v[162:165], off offset:256
.LBB0_539:
	s_andn2_b64 vcc, exec, s[24:25]
	s_cbranch_vccnz .LBB0_541
	s_nop 1
	ds_bpermute_b32 v162, v244, v212
	ds_bpermute_b32 v163, v244, v213
	ds_bpermute_b32 v164, v244, v214
	ds_bpermute_b32 v165, v244, v215
	s_waitcnt lgkmcnt(0)
	v_lshlrev_b32_e32 v148, 16, v164
	v_and_b32_e32 v149, 0xffff0000, v164
	v_max_f32_e32 v148, v148, v148
	v_max_f32_e32 v149, v149, v149
	v_lshlrev_b32_e32 v144, 16, v162
	v_and_b32_e32 v145, 0xffff0000, v162
	v_max_f32_e32 v148, 0xda24260, v148
	v_max_f32_e32 v149, 0xda24260, v149
	v_max_f32_e32 v144, v144, v144
	v_rcp_f32_e32 v148, v148
	v_max_f32_e32 v145, v145, v145
	v_rcp_f32_e32 v149, v149
	v_max_f32_e32 v144, 0xda24260, v144
	v_max_f32_e32 v145, 0xda24260, v145
	v_rcp_f32_e32 v144, v144
	v_rcp_f32_e32 v145, v145
	v_lshlrev_b32_e32 v162, 16, v165
	v_pk_mul_f32 v[148:149], v[148:149], v[152:153]
	v_max_f32_e32 v153, v162, v162
	v_lshlrev_b32_e32 v156, 16, v163
	v_and_b32_e32 v157, 0xffff0000, v163
	v_max_f32_e32 v153, 0xda24260, v153
	v_pk_mul_f32 v[144:145], v[144:145], v[154:155]
	v_max_f32_e32 v152, v156, v156
	v_rcp_f32_e32 v154, v153
	v_max_f32_e32 v153, v157, v157
	v_max_f32_e32 v152, 0xda24260, v152
	v_max_f32_e32 v153, 0xda24260, v153
	v_rcp_f32_e32 v152, v152
	v_rcp_f32_e32 v153, v153
	v_and_b32_e32 v163, 0xffff0000, v165
	v_pk_mul_f32 v[80:81], v[80:81], v[144:145]
	v_pk_mul_f32 v[76:77], v[76:77], v[148:149]
	v_pk_mul_f32 v[150:151], v[152:153], v[150:151]
	v_max_f32_e32 v152, v163, v163
	v_max_f32_e32 v152, 0xda24260, v152
	v_rcp_f32_e32 v155, v152
	v_pk_mul_f32 v[82:83], v[82:83], v[150:151]
	v_pk_mul_f32 v[146:147], v[154:155], v[146:147]
	s_nop 0
	v_pk_mul_f32 v[78:79], v[78:79], v[146:147]
.LBB0_541:
	v_or_b32_e32 v144, 48, v2
	v_ashrrev_i32_e32 v145, 31, v144
	v_lshlrev_b64 v[148:149], 11, v[144:145]
	v_lshl_add_u64 v[144:145], s[22:23], 0, v[148:149]
	v_lshl_add_u64 v[146:147], v[144:145], 0, v[0:1]
	v_lshl_add_u64 v[144:145], s[2:3], 0, v[148:149]
	s_and_b64 vcc, exec, s[6:7]
	v_lshl_add_u64 v[144:145], v[144:145], 0, v[0:1]
	s_mov_b64 s[24:25], -1
	s_nop 1
	ds_bpermute_b32 v162, v244, v216
	ds_bpermute_b32 v163, v244, v217
	ds_bpermute_b32 v164, v244, v218
	ds_bpermute_b32 v165, v244, v219
	s_waitcnt lgkmcnt(0)
	v_lshlrev_b32_e32 v156, 16, v162
	v_and_b32_e32 v157, 0xffff0000, v162
	v_lshlrev_b32_e32 v152, 16, v163
	v_and_b32_e32 v153, 0xffff0000, v163
	v_lshlrev_b32_e32 v154, 16, v164
	v_and_b32_e32 v155, 0xffff0000, v164
	v_lshlrev_b32_e32 v150, 16, v165
	v_and_b32_e32 v151, 0xffff0000, v165
	s_cbranch_vccnz .LBB0_543
	v_pk_mul_f32 v[164:165], v[106:107], v[152:153]
	v_pk_mul_f32 v[162:163], v[104:105], v[156:157]
	v_pk_mul_f32 v[192:193], v[102:103], v[150:151]
	v_pk_mul_f32 v[194:195], v[100:101], v[154:155]
	v_cvt_pk_bf16_f32 v162, v162, v163
	v_cvt_pk_bf16_f32 v163, v164, v165
	v_cvt_pk_bf16_f32 v164, v194, v195
	v_cvt_pk_bf16_f32 v165, v192, v193
	s_mov_b64 s[24:25], 0
	global_store_dwordx4 v[144:145], v[162:165], off
.LBB0_543:
	v_lshl_add_u64 v[148:149], s[20:21], 0, v[148:149]
	s_andn2_b64 vcc, exec, s[24:25]
	v_lshl_add_u64 v[148:149], v[148:149], 0, v[0:1]
	s_cbranch_vccnz .LBB0_545
	s_nop 1
	ds_bpermute_b32 v162, v244, v220
	ds_bpermute_b32 v163, v244, v221
	ds_bpermute_b32 v164, v244, v222
	ds_bpermute_b32 v165, v244, v223
	s_waitcnt lgkmcnt(0)
	v_lshlrev_b32_e32 v193, 16, v163
	v_and_b32_e32 v194, 0xffff0000, v163
	v_lshlrev_b32_e32 v163, 16, v164
	v_max_f32_e32 v163, v163, v163
	v_lshlrev_b32_e32 v182, 16, v162
	v_and_b32_e32 v192, 0xffff0000, v162
	v_max_f32_e32 v163, 0xda24260, v163
	v_and_b32_e32 v195, 0xffff0000, v164
	v_max_f32_e32 v162, v182, v182
	v_rcp_f32_e32 v164, v163
	v_max_f32_e32 v163, v192, v192
	v_max_f32_e32 v162, 0xda24260, v162
	v_max_f32_e32 v163, 0xda24260, v163
	v_rcp_f32_e32 v162, v162
	v_rcp_f32_e32 v163, v163
	v_lshlrev_b32_e32 v196, 16, v165
	v_and_b32_e32 v197, 0xffff0000, v165
	v_pk_mul_f32 v[156:157], v[162:163], v[156:157]
	v_max_f32_e32 v162, v195, v195
	v_max_f32_e32 v162, 0xda24260, v162
	v_rcp_f32_e32 v165, v162
	v_max_f32_e32 v163, v196, v196
	v_max_f32_e32 v163, 0xda24260, v163
	v_max_f32_e32 v162, v193, v193
	v_pk_mul_f32 v[154:155], v[164:165], v[154:155]
	v_rcp_f32_e32 v164, v163
	v_max_f32_e32 v163, v194, v194
	v_max_f32_e32 v162, 0xda24260, v162
	v_max_f32_e32 v163, 0xda24260, v163
	v_rcp_f32_e32 v162, v162
	v_rcp_f32_e32 v163, v163
	v_pk_mul_f32 v[104:105], v[104:105], v[156:157]
	v_pk_mul_f32 v[100:101], v[100:101], v[154:155]
	v_pk_mul_f32 v[152:153], v[162:163], v[152:153]
	v_max_f32_e32 v162, v197, v197
	v_max_f32_e32 v162, 0xda24260, v162
	v_rcp_f32_e32 v165, v162
	v_pk_mul_f32 v[106:107], v[106:107], v[152:153]
	v_pk_mul_f32 v[150:151], v[164:165], v[150:151]
	s_nop 0
	v_pk_mul_f32 v[102:103], v[102:103], v[150:151]
; #define GAS __attribute__((address_space(1)))
; __device__ __forceinline__ unsigned cvt_pk_bf16(float lo, float hi) { f32x2 v = {lo, hi}; bf16x2_t b = __builtin_convertvector(v, bf16x2_t); return __builtin_bit_cast(unsigned, b); }
; __device__ __forceinline__ float bf_lo(unsigned u) { return __uint_as_float(u << 16); }
; __device__ __forceinline__ float bf_hi(unsigned u) { return __uint_as_float(u & 0xffff0000u); }
;     __device__ __forceinline__ void operator()(f32x4 (&acc)[2][2][4][2], const Unit& u, int wr, int wc, int fr, int fq) const {
;         const int br = u.pm >> 7, pm = u.pm & 127, pn = u.pn & 3;
;         const int row0 = pm * BM + wr * 64 + fr; const int col0 = pn * BM + wc * 32 + 8 * fq;
; #pragma unroll
;         for (int ai = 0; ai < 2; ++ai)
; #pragma unroll
;             for (int m = 0; m < 4; ++m) { const int row = row0 + ai * HALF + m * 16; const GAS bf16_t* gp = ((br < 2) ? g01 + (size_t)br * MROWS * 1024 : g2) + (size_t)row * 1024 + col0; const GAS bf16_t* gn = ((br == 0) ? g01 + (size_t)MROWS * 1024 : g2) + (size_t)row * 1024 + col0; GAS bf16_t* mp = Mg + (size_t)row * 1024 + col0;
; #pragma unroll
;                 for (int bj = 0; bj < 2; ++bj) { const u32x4 g = *(const GAS u32x4*)(gp + bj * HALF);
;                     f32x4 s0 = {bf_lo(g.x), bf_hi(g.x), bf_lo(g.y), bf_hi(g.y)}, s1 = {bf_lo(g.z), bf_hi(g.z), bf_lo(g.w), bf_hi(g.w)};
;                     if (br < 2) { const u32x4 h = *(const GAS u32x4*)(gn + bj * HALF);
;                         const f32x4 d0 = {bf_lo(h.x), bf_hi(h.x), bf_lo(h.y), bf_hi(h.y)}, d1 = {bf_lo(h.z), bf_hi(h.z), bf_lo(h.w), bf_hi(h.w)};
; #pragma unroll
;                         for (int e = 0; e < 4; ++e) { s0[e] *= __builtin_amdgcn_rcpf(fmaxf(d0[e], 1e-30f)); s1[e] *= __builtin_amdgcn_rcpf(fmaxf(d1[e], 1e-30f)); }
;                         acc[ai][bj][m][0] *= s0; acc[ai][bj][m][1] *= s1;
;                     } else { const f32x4 v0 = acc[ai][bj][m][0] * s0, v1 = acc[ai][bj][m][1] * s1;
;                         u32x4 w; w.x = cvt_pk_bf16(v0[0], v0[1]); w.y = cvt_pk_bf16(v0[2], v0[3]); w.z = cvt_pk_bf16(v1[0], v1[1]); w.w = cvt_pk_bf16(v1[2], v1[3]);
;                         *(GAS u32x4*)(mp + bj * HALF) = w; } } }
.LBB0_545:
	s_and_b64 vcc, exec, s[6:7]
	s_mov_b64 s[24:25], -1
	s_nop 1
	ds_bpermute_b32 v162, v244, v224
	ds_bpermute_b32 v163, v244, v225
	ds_bpermute_b32 v164, v244, v226
	ds_bpermute_b32 v165, v244, v227
	s_waitcnt lgkmcnt(0)
	v_lshlrev_b32_e32 v154, 16, v162
	v_and_b32_e32 v155, 0xffff0000, v162
	v_lshlrev_b32_e32 v150, 16, v163
	v_and_b32_e32 v151, 0xffff0000, v163
	v_lshlrev_b32_e32 v152, 16, v164
	v_and_b32_e32 v153, 0xffff0000, v164
	v_lshlrev_b32_e32 v146, 16, v165
	v_and_b32_e32 v147, 0xffff0000, v165
	s_cbranch_vccnz .LBB0_547
	v_pk_mul_f32 v[156:157], v[74:75], v[150:151]
	v_pk_mul_f32 v[162:163], v[72:73], v[154:155]
	v_pk_mul_f32 v[192:193], v[70:71], v[146:147]
	v_pk_mul_f32 v[164:165], v[68:69], v[152:153]
	v_cvt_pk_bf16_f32 v162, v162, v163
	v_cvt_pk_bf16_f32 v163, v156, v157
	v_cvt_pk_bf16_f32 v164, v164, v165
	v_cvt_pk_bf16_f32 v165, v192, v193
	s_mov_b64 s[24:25], 0
	global_store_dwordx4 v[144:145], v[162:165], off offset:256
.LBB0_547:
	s_andn2_b64 vcc, exec, s[24:25]
	s_cbranch_vccnz .LBB0_549
	s_nop 1
	ds_bpermute_b32 v162, v244, v228
	ds_bpermute_b32 v163, v244, v229
	ds_bpermute_b32 v164, v244, v230
	ds_bpermute_b32 v165, v244, v231
	s_waitcnt lgkmcnt(0)
	v_lshlrev_b32_e32 v148, 16, v164
	v_and_b32_e32 v149, 0xffff0000, v164
	v_max_f32_e32 v148, v148, v148
	v_max_f32_e32 v149, v149, v149
	v_lshlrev_b32_e32 v144, 16, v162
	v_and_b32_e32 v145, 0xffff0000, v162
	v_max_f32_e32 v148, 0xda24260, v148
	v_max_f32_e32 v149, 0xda24260, v149
	v_max_f32_e32 v144, v144, v144
	v_rcp_f32_e32 v148, v148
	v_max_f32_e32 v145, v145, v145
	v_rcp_f32_e32 v149, v149
	v_max_f32_e32 v144, 0xda24260, v144
	v_max_f32_e32 v145, 0xda24260, v145
	v_rcp_f32_e32 v144, v144
	v_rcp_f32_e32 v145, v145
	v_lshlrev_b32_e32 v162, 16, v165
	v_pk_mul_f32 v[148:149], v[148:149], v[152:153]
	v_max_f32_e32 v153, v162, v162
	v_lshlrev_b32_e32 v156, 16, v163
	v_and_b32_e32 v157, 0xffff0000, v163
	v_max_f32_e32 v153, 0xda24260, v153
	v_pk_mul_f32 v[144:145], v[144:145], v[154:155]
	v_max_f32_e32 v152, v156, v156
	v_rcp_f32_e32 v154, v153
	v_max_f32_e32 v153, v157, v157
	v_max_f32_e32 v152, 0xda24260, v152
	v_max_f32_e32 v153, 0xda24260, v153
	v_rcp_f32_e32 v152, v152
	v_rcp_f32_e32 v153, v153
	v_and_b32_e32 v163, 0xffff0000, v165
	v_pk_mul_f32 v[72:73], v[72:73], v[144:145]
	v_pk_mul_f32 v[68:69], v[68:69], v[148:149]
	v_pk_mul_f32 v[150:151], v[152:153], v[150:151]
	v_max_f32_e32 v152, v163, v163
	v_max_f32_e32 v152, 0xda24260, v152
	v_rcp_f32_e32 v155, v152
	v_pk_mul_f32 v[74:75], v[74:75], v[150:151]
	v_pk_mul_f32 v[146:147], v[154:155], v[146:147]
	s_nop 0
	v_pk_mul_f32 v[70:71], v[70:71], v[146:147]
.LBB0_549:
	v_lshlrev_b64 v[144:145], 11, v[2:3]
	s_mov_b64 s[24:25], 0x40000
	v_lshl_add_u64 v[148:149], v[144:145], 0, s[24:25]
	v_lshl_add_u64 v[144:145], s[22:23], 0, v[148:149]
	v_lshl_add_u64 v[146:147], v[144:145], 0, v[0:1]
	v_lshl_add_u64 v[144:145], s[2:3], 0, v[148:149]
	s_and_b64 vcc, exec, s[6:7]
	v_lshl_add_u64 v[144:145], v[144:145], 0, v[0:1]
	s_mov_b64 s[24:25], -1
	v_add_u32_e32 v199, 0x40000, v198
	global_load_dwordx4 v[200:203], v199, s[22:23]
	global_load_dwordx4 v[204:207], v199, s[20:21]
	global_load_dwordx4 v[208:211], v199, s[22:23] offset:256
	global_load_dwordx4 v[212:215], v199, s[20:21] offset:256
	v_add_u32_e32 v199, 0x48000, v198
	global_load_dwordx4 v[216:219], v199, s[22:23]
	global_load_dwordx4 v[220:223], v199, s[20:21]
	global_load_dwordx4 v[224:227], v199, s[22:23] offset:256
	global_load_dwordx4 v[228:231], v199, s[20:21] offset:256
	s_waitcnt vmcnt(0)
	s_nop 1
	ds_bpermute_b32 v162, v244, v200
	ds_bpermute_b32 v163, v244, v201
	ds_bpermute_b32 v164, v244, v202
	ds_bpermute_b32 v165, v244, v203
	s_waitcnt lgkmcnt(0)
	v_lshlrev_b32_e32 v156, 16, v162
	v_and_b32_e32 v157, 0xffff0000, v162
	v_lshlrev_b32_e32 v152, 16, v163
	v_and_b32_e32 v153, 0xffff0000, v163
	v_lshlrev_b32_e32 v154, 16, v164
	v_and_b32_e32 v155, 0xffff0000, v164
	v_lshlrev_b32_e32 v150, 16, v165
	v_and_b32_e32 v151, 0xffff0000, v165
	s_cbranch_vccnz .LBB0_551
	v_pk_mul_f32 v[164:165], v[66:67], v[152:153]
	v_pk_mul_f32 v[162:163], v[64:65], v[156:157]
	v_pk_mul_f32 v[192:193], v[62:63], v[150:151]
	v_pk_mul_f32 v[194:195], v[60:61], v[154:155]
	v_cvt_pk_bf16_f32 v162, v162, v163
	v_cvt_pk_bf16_f32 v163, v164, v165
	v_cvt_pk_bf16_f32 v164, v194, v195
	v_cvt_pk_bf16_f32 v165, v192, v193
	s_mov_b64 s[24:25], 0
	global_store_dwordx4 v[144:145], v[162:165], off
.LBB0_551:
	v_lshl_add_u64 v[148:149], s[20:21], 0, v[148:149]
	s_andn2_b64 vcc, exec, s[24:25]
	v_lshl_add_u64 v[148:149], v[148:149], 0, v[0:1]
	s_cbranch_vccnz .LBB0_553
	s_nop 1
	ds_bpermute_b32 v162, v244, v204
	ds_bpermute_b32 v163, v244, v205
	ds_bpermute_b32 v164, v244, v206
	ds_bpermute_b32 v165, v244, v207
	s_waitcnt lgkmcnt(0)
	v_lshlrev_b32_e32 v193, 16, v163
	v_and_b32_e32 v194, 0xffff0000, v163
	v_lshlrev_b32_e32 v163, 16, v164
	v_max_f32_e32 v163, v163, v163
	v_lshlrev_b32_e32 v182, 16, v162
	v_and_b32_e32 v192, 0xffff0000, v162
	v_max_f32_e32 v163, 0xda24260, v163
	v_and_b32_e32 v195, 0xffff0000, v164
	v_max_f32_e32 v162, v182, v182
	v_rcp_f32_e32 v164, v163
	v_max_f32_e32 v163, v192, v192
	v_max_f32_e32 v162, 0xda24260, v162
	v_max_f32_e32 v163, 0xda24260, v163
	v_rcp_f32_e32 v162, v162
	v_rcp_f32_e32 v163, v163
	v_lshlrev_b32_e32 v196, 16, v165
	v_and_b32_e32 v197, 0xffff0000, v165
	v_pk_mul_f32 v[156:157], v[162:163], v[156:157]
	v_max_f32_e32 v162, v195, v195
	v_max_f32_e32 v162, 0xda24260, v162
	v_rcp_f32_e32 v165, v162
	v_max_f32_e32 v163, v196, v196
	v_max_f32_e32 v163, 0xda24260, v163
	v_max_f32_e32 v162, v193, v193
	v_pk_mul_f32 v[154:155], v[164:165], v[154:155]
	v_rcp_f32_e32 v164, v163
	v_max_f32_e32 v163, v194, v194
	v_max_f32_e32 v162, 0xda24260, v162
	v_max_f32_e32 v163, 0xda24260, v163
	v_rcp_f32_e32 v162, v162
	v_rcp_f32_e32 v163, v163
	v_pk_mul_f32 v[64:65], v[64:65], v[156:157]
	v_pk_mul_f32 v[60:61], v[60:61], v[154:155]
	v_pk_mul_f32 v[152:153], v[162:163], v[152:153]
	v_max_f32_e32 v162, v197, v197
	v_max_f32_e32 v162, 0xda24260, v162
	v_rcp_f32_e32 v165, v162
	v_pk_mul_f32 v[66:67], v[66:67], v[152:153]
	v_pk_mul_f32 v[150:151], v[164:165], v[150:151]
	s_nop 0
	v_pk_mul_f32 v[62:63], v[62:63], v[150:151]
; #define GAS __attribute__((address_space(1)))
; __device__ __forceinline__ unsigned cvt_pk_bf16(float lo, float hi) { f32x2 v = {lo, hi}; bf16x2_t b = __builtin_convertvector(v, bf16x2_t); return __builtin_bit_cast(unsigned, b); }
; __device__ __forceinline__ float bf_lo(unsigned u) { return __uint_as_float(u << 16); }
; __device__ __forceinline__ float bf_hi(unsigned u) { return __uint_as_float(u & 0xffff0000u); }
;     __device__ __forceinline__ void operator()(f32x4 (&acc)[2][2][4][2], const Unit& u, int wr, int wc, int fr, int fq) const {
;         const int br = u.pm >> 7, pm = u.pm & 127, pn = u.pn & 3;
;         const int row0 = pm * BM + wr * 64 + fr; const int col0 = pn * BM + wc * 32 + 8 * fq;
; #pragma unroll
;         for (int ai = 0; ai < 2; ++ai)
; #pragma unroll
;             for (int m = 0; m < 4; ++m) { const int row = row0 + ai * HALF + m * 16; const GAS bf16_t* gp = ((br < 2) ? g01 + (size_t)br * MROWS * 1024 : g2) + (size_t)row * 1024 + col0; const GAS bf16_t* gn = ((br == 0) ? g01 + (size_t)MROWS * 1024 : g2) + (size_t)row * 1024 + col0; GAS bf16_t* mp = Mg + (size_t)row * 1024 + col0;
; #pragma unroll
;                 for (int bj = 0; bj < 2; ++bj) { const u32x4 g = *(const GAS u32x4*)(gp + bj * HALF);
;                     f32x4 s0 = {bf_lo(g.x), bf_hi(g.x), bf_lo(g.y), bf_hi(g.y)}, s1 = {bf_lo(g.z), bf_hi(g.z), bf_lo(g.w), bf_hi(g.w)};
;                     if (br < 2) { const u32x4 h = *(const GAS u32x4*)(gn + bj * HALF);
;                         const f32x4 d0 = {bf_lo(h.x), bf_hi(h.x), bf_lo(h.y), bf_hi(h.y)}, d1 = {bf_lo(h.z), bf_hi(h.z), bf_lo(h.w), bf_hi(h.w)};
; #pragma unroll
;                         for (int e = 0; e < 4; ++e) { s0[e] *= __builtin_amdgcn_rcpf(fmaxf(d0[e], 1e-30f)); s1[e] *= __builtin_amdgcn_rcpf(fmaxf(d1[e], 1e-30f)); }
;                         acc[ai][bj][m][0] *= s0; acc[ai][bj][m][1] *= s1;
;                     } else { const f32x4 v0 = acc[ai][bj][m][0] * s0, v1 = acc[ai][bj][m][1] * s1;
;                         u32x4 w; w.x = cvt_pk_bf16(v0[0], v0[1]); w.y = cvt_pk_bf16(v0[2], v0[3]); w.z = cvt_pk_bf16(v1[0], v1[1]); w.w = cvt_pk_bf16(v1[2], v1[3]);
;                         *(GAS u32x4*)(mp + bj * HALF) = w; } } }
.LBB0_553:
	s_and_b64 vcc, exec, s[6:7]
	s_mov_b64 s[24:25], -1
	s_nop 1
	ds_bpermute_b32 v162, v244, v208
	ds_bpermute_b32 v163, v244, v209
	ds_bpermute_b32 v164, v244, v210
	ds_bpermute_b32 v165, v244, v211
	s_waitcnt lgkmcnt(0)
	v_lshlrev_b32_e32 v154, 16, v162
	v_and_b32_e32 v155, 0xffff0000, v162
	v_lshlrev_b32_e32 v150, 16, v163
	v_and_b32_e32 v151, 0xffff0000, v163
	v_lshlrev_b32_e32 v152, 16, v164
	v_and_b32_e32 v153, 0xffff0000, v164
	v_lshlrev_b32_e32 v146, 16, v165
	v_and_b32_e32 v147, 0xffff0000, v165
	s_cbranch_vccnz .LBB0_555
	v_pk_mul_f32 v[156:157], v[34:35], v[150:151]
	v_pk_mul_f32 v[162:163], v[32:33], v[154:155]
	v_pk_mul_f32 v[192:193], v[30:31], v[146:147]
	v_pk_mul_f32 v[164:165], v[28:29], v[152:153]
	v_cvt_pk_bf16_f32 v162, v162, v163
	v_cvt_pk_bf16_f32 v163, v156, v157
	v_cvt_pk_bf16_f32 v164, v164, v165
	v_cvt_pk_bf16_f32 v165, v192, v193
	s_mov_b64 s[24:25], 0
	global_store_dwordx4 v[144:145], v[162:165], off offset:256
.LBB0_555:
	s_andn2_b64 vcc, exec, s[24:25]
	s_cbranch_vccnz .LBB0_557
	s_nop 1
	ds_bpermute_b32 v162, v244, v212
	ds_bpermute_b32 v163, v244, v213
	ds_bpermute_b32 v164, v244, v214
	ds_bpermute_b32 v165, v244, v215
	s_waitcnt lgkmcnt(0)
	v_lshlrev_b32_e32 v148, 16, v164
	v_and_b32_e32 v149, 0xffff0000, v164
	v_max_f32_e32 v148, v148, v148
	v_max_f32_e32 v149, v149, v149
	v_lshlrev_b32_e32 v144, 16, v162
	v_and_b32_e32 v145, 0xffff0000, v162
	v_max_f32_e32 v148, 0xda24260, v148
	v_max_f32_e32 v149, 0xda24260, v149
	v_max_f32_e32 v144, v144, v144
	v_rcp_f32_e32 v148, v148
	v_max_f32_e32 v145, v145, v145
	v_rcp_f32_e32 v149, v149
	v_max_f32_e32 v144, 0xda24260, v144
	v_max_f32_e32 v145, 0xda24260, v145
	v_rcp_f32_e32 v144, v144
	v_rcp_f32_e32 v145, v145
	v_lshlrev_b32_e32 v162, 16, v165
	v_pk_mul_f32 v[148:149], v[148:149], v[152:153]
	v_max_f32_e32 v153, v162, v162
	v_lshlrev_b32_e32 v156, 16, v163
	v_and_b32_e32 v157, 0xffff0000, v163
	v_max_f32_e32 v153, 0xda24260, v153
	v_pk_mul_f32 v[144:145], v[144:145], v[154:155]
	v_max_f32_e32 v152, v156, v156
	v_rcp_f32_e32 v154, v153
	v_max_f32_e32 v153, v157, v157
	v_max_f32_e32 v152, 0xda24260, v152
	v_max_f32_e32 v153, 0xda24260, v153
	v_rcp_f32_e32 v152, v152
	v_rcp_f32_e32 v153, v153
	v_and_b32_e32 v163, 0xffff0000, v165
	v_pk_mul_f32 v[32:33], v[32:33], v[144:145]
	v_pk_mul_f32 v[28:29], v[28:29], v[148:149]
	v_pk_mul_f32 v[150:151], v[152:153], v[150:151]
	v_max_f32_e32 v152, v163, v163
	v_max_f32_e32 v152, 0xda24260, v152
	v_rcp_f32_e32 v155, v152
	v_pk_mul_f32 v[34:35], v[34:35], v[150:151]
	v_pk_mul_f32 v[146:147], v[154:155], v[146:147]
	s_nop 0
	v_pk_mul_f32 v[30:31], v[30:31], v[146:147]
.LBB0_557:
	v_lshlrev_b64 v[144:145], 11, v[2:3]
	s_mov_b64 s[24:25], 0x48000
	v_lshl_add_u64 v[148:149], v[144:145], 0, s[24:25]
	v_lshl_add_u64 v[144:145], s[22:23], 0, v[148:149]
	v_lshl_add_u64 v[146:147], v[144:145], 0, v[0:1]
	v_lshl_add_u64 v[144:145], s[2:3], 0, v[148:149]
	s_and_b64 vcc, exec, s[6:7]
	v_lshl_add_u64 v[144:145], v[144:145], 0, v[0:1]
	s_mov_b64 s[24:25], -1
	s_nop 1
	ds_bpermute_b32 v162, v244, v216
	ds_bpermute_b32 v163, v244, v217
	ds_bpermute_b32 v164, v244, v218
	ds_bpermute_b32 v165, v244, v219
	s_waitcnt lgkmcnt(0)
	v_lshlrev_b32_e32 v156, 16, v162
	v_and_b32_e32 v157, 0xffff0000, v162
	v_lshlrev_b32_e32 v152, 16, v163
	v_and_b32_e32 v153, 0xffff0000, v163
	v_lshlrev_b32_e32 v154, 16, v164
	v_and_b32_e32 v155, 0xffff0000, v164
	v_lshlrev_b32_e32 v150, 16, v165
	v_and_b32_e32 v151, 0xffff0000, v165
	s_cbranch_vccnz .LBB0_559
	v_pk_mul_f32 v[164:165], v[58:59], v[152:153]
	v_pk_mul_f32 v[162:163], v[56:57], v[156:157]
	v_pk_mul_f32 v[192:193], v[54:55], v[150:151]
	v_pk_mul_f32 v[194:195], v[52:53], v[154:155]
	v_cvt_pk_bf16_f32 v162, v162, v163
	v_cvt_pk_bf16_f32 v163, v164, v165
	v_cvt_pk_bf16_f32 v164, v194, v195
	v_cvt_pk_bf16_f32 v165, v192, v193
	s_mov_b64 s[24:25], 0
	global_store_dwordx4 v[144:145], v[162:165], off
.LBB0_559:
	v_lshl_add_u64 v[148:149], s[20:21], 0, v[148:149]
	s_andn2_b64 vcc, exec, s[24:25]
	v_lshl_add_u64 v[148:149], v[148:149], 0, v[0:1]
	s_cbranch_vccnz .LBB0_561
	s_nop 1
	ds_bpermute_b32 v162, v244, v220
	ds_bpermute_b32 v163, v244, v221
	ds_bpermute_b32 v164, v244, v222
	ds_bpermute_b32 v165, v244, v223
	s_waitcnt lgkmcnt(0)
	v_lshlrev_b32_e32 v193, 16, v163
	v_and_b32_e32 v194, 0xffff0000, v163
	v_lshlrev_b32_e32 v163, 16, v164
	v_max_f32_e32 v163, v163, v163
	v_lshlrev_b32_e32 v182, 16, v162
	v_and_b32_e32 v192, 0xffff0000, v162
	v_max_f32_e32 v163, 0xda24260, v163
	v_and_b32_e32 v195, 0xffff0000, v164
	v_max_f32_e32 v162, v182, v182
	v_rcp_f32_e32 v164, v163
	v_max_f32_e32 v163, v192, v192
	v_max_f32_e32 v162, 0xda24260, v162
	v_max_f32_e32 v163, 0xda24260, v163
	v_rcp_f32_e32 v162, v162
	v_rcp_f32_e32 v163, v163
	v_lshlrev_b32_e32 v196, 16, v165
	v_and_b32_e32 v197, 0xffff0000, v165
	v_pk_mul_f32 v[156:157], v[162:163], v[156:157]
	v_max_f32_e32 v162, v195, v195
	v_max_f32_e32 v162, 0xda24260, v162
	v_rcp_f32_e32 v165, v162
	v_max_f32_e32 v163, v196, v196
	v_max_f32_e32 v163, 0xda24260, v163
	v_max_f32_e32 v162, v193, v193
	v_pk_mul_f32 v[154:155], v[164:165], v[154:155]
	v_rcp_f32_e32 v164, v163
	v_max_f32_e32 v163, v194, v194
	v_max_f32_e32 v162, 0xda24260, v162
	v_max_f32_e32 v163, 0xda24260, v163
	v_rcp_f32_e32 v162, v162
	v_rcp_f32_e32 v163, v163
	v_pk_mul_f32 v[56:57], v[56:57], v[156:157]
	v_pk_mul_f32 v[52:53], v[52:53], v[154:155]
	v_pk_mul_f32 v[152:153], v[162:163], v[152:153]
	v_max_f32_e32 v162, v197, v197
	v_max_f32_e32 v162, 0xda24260, v162
	v_rcp_f32_e32 v165, v162
	v_pk_mul_f32 v[58:59], v[58:59], v[152:153]
	v_pk_mul_f32 v[150:151], v[164:165], v[150:151]
	s_nop 0
	v_pk_mul_f32 v[54:55], v[54:55], v[150:151]
; #define GAS __attribute__((address_space(1)))
; __device__ __forceinline__ unsigned cvt_pk_bf16(float lo, float hi) { f32x2 v = {lo, hi}; bf16x2_t b = __builtin_convertvector(v, bf16x2_t); return __builtin_bit_cast(unsigned, b); }
; __device__ __forceinline__ float bf_lo(unsigned u) { return __uint_as_float(u << 16); }
; __device__ __forceinline__ float bf_hi(unsigned u) { return __uint_as_float(u & 0xffff0000u); }
;     __device__ __forceinline__ void operator()(f32x4 (&acc)[2][2][4][2], const Unit& u, int wr, int wc, int fr, int fq) const {
;         const int br = u.pm >> 7, pm = u.pm & 127, pn = u.pn & 3;
;         const int row0 = pm * BM + wr * 64 + fr; const int col0 = pn * BM + wc * 32 + 8 * fq;
; #pragma unroll
;         for (int ai = 0; ai < 2; ++ai)
; #pragma unroll
;             for (int m = 0; m < 4; ++m) { const int row = row0 + ai * HALF + m * 16; const GAS bf16_t* gp = ((br < 2) ? g01 + (size_t)br * MROWS * 1024 : g2) + (size_t)row * 1024 + col0; const GAS bf16_t* gn = ((br == 0) ? g01 + (size_t)MROWS * 1024 : g2) + (size_t)row * 1024 + col0; GAS bf16_t* mp = Mg + (size_t)row * 1024 + col0;
; #pragma unroll
;                 for (int bj = 0; bj < 2; ++bj) { const u32x4 g = *(const GAS u32x4*)(gp + bj * HALF);
;                     f32x4 s0 = {bf_lo(g.x), bf_hi(g.x), bf_lo(g.y), bf_hi(g.y)}, s1 = {bf_lo(g.z), bf_hi(g.z), bf_lo(g.w), bf_hi(g.w)};
;                     if (br < 2) { const u32x4 h = *(const GAS u32x4*)(gn + bj * HALF);
;                         const f32x4 d0 = {bf_lo(h.x), bf_hi(h.x), bf_lo(h.y), bf_hi(h.y)}, d1 = {bf_lo(h.z), bf_hi(h.z), bf_lo(h.w), bf_hi(h.w)};
; #pragma unroll
;                         for (int e = 0; e < 4; ++e) { s0[e] *= __builtin_amdgcn_rcpf(fmaxf(d0[e], 1e-30f)); s1[e] *= __builtin_amdgcn_rcpf(fmaxf(d1[e], 1e-30f)); }
;                         acc[ai][bj][m][0] *= s0; acc[ai][bj][m][1] *= s1;
;                     } else { const f32x4 v0 = acc[ai][bj][m][0] * s0, v1 = acc[ai][bj][m][1] * s1;
;                         u32x4 w; w.x = cvt_pk_bf16(v0[0], v0[1]); w.y = cvt_pk_bf16(v0[2], v0[3]); w.z = cvt_pk_bf16(v1[0], v1[1]); w.w = cvt_pk_bf16(v1[2], v1[3]);
;                         *(GAS u32x4*)(mp + bj * HALF) = w; } } }
.LBB0_561:
	s_and_b64 vcc, exec, s[6:7]
	s_mov_b64 s[24:25], -1
	s_nop 1
	ds_bpermute_b32 v162, v244, v224
	ds_bpermute_b32 v163, v244, v225
	ds_bpermute_b32 v164, v244, v226
	ds_bpermute_b32 v165, v244, v227
	s_waitcnt lgkmcnt(0)
	v_lshlrev_b32_e32 v154, 16, v162
	v_and_b32_e32 v155, 0xffff0000, v162
	v_lshlrev_b32_e32 v150, 16, v163
	v_and_b32_e32 v151, 0xffff0000, v163
	v_lshlrev_b32_e32 v152, 16, v164
	v_and_b32_e32 v153, 0xffff0000, v164
	v_lshlrev_b32_e32 v146, 16, v165
	v_and_b32_e32 v147, 0xffff0000, v165
	s_cbranch_vccnz .LBB0_563
	v_pk_mul_f32 v[156:157], v[26:27], v[150:151]
	v_pk_mul_f32 v[162:163], v[24:25], v[154:155]
	v_pk_mul_f32 v[192:193], v[22:23], v[146:147]
	v_pk_mul_f32 v[164:165], v[20:21], v[152:153]
	v_cvt_pk_bf16_f32 v162, v162, v163
	v_cvt_pk_bf16_f32 v163, v156, v157
	v_cvt_pk_bf16_f32 v164, v164, v165
	v_cvt_pk_bf16_f32 v165, v192, v193
	s_mov_b64 s[24:25], 0
	global_store_dwordx4 v[144:145], v[162:165], off offset:256
.LBB0_563:
	s_andn2_b64 vcc, exec, s[24:25]
	s_cbranch_vccnz .LBB0_565
	s_nop 1
	ds_bpermute_b32 v162, v244, v228
	ds_bpermute_b32 v163, v244, v229
	ds_bpermute_b32 v164, v244, v230
	ds_bpermute_b32 v165, v244, v231
	s_waitcnt lgkmcnt(0)
	v_lshlrev_b32_e32 v148, 16, v164
	v_and_b32_e32 v149, 0xffff0000, v164
	v_max_f32_e32 v148, v148, v148
	v_max_f32_e32 v149, v149, v149
	v_lshlrev_b32_e32 v144, 16, v162
	v_and_b32_e32 v145, 0xffff0000, v162
	v_max_f32_e32 v148, 0xda24260, v148
	v_max_f32_e32 v149, 0xda24260, v149
	v_max_f32_e32 v144, v144, v144
	v_rcp_f32_e32 v148, v148
	v_max_f32_e32 v145, v145, v145
	v_rcp_f32_e32 v149, v149
	v_max_f32_e32 v144, 0xda24260, v144
	v_max_f32_e32 v145, 0xda24260, v145
	v_rcp_f32_e32 v144, v144
	v_rcp_f32_e32 v145, v145
	v_lshlrev_b32_e32 v162, 16, v165
	v_pk_mul_f32 v[148:149], v[148:149], v[152:153]
	v_max_f32_e32 v153, v162, v162
	v_lshlrev_b32_e32 v156, 16, v163
	v_and_b32_e32 v157, 0xffff0000, v163
	v_max_f32_e32 v153, 0xda24260, v153
	v_pk_mul_f32 v[144:145], v[144:145], v[154:155]
	v_max_f32_e32 v152, v156, v156
	v_rcp_f32_e32 v154, v153
	v_max_f32_e32 v153, v157, v157
	v_max_f32_e32 v152, 0xda24260, v152
	v_max_f32_e32 v153, 0xda24260, v153
	v_rcp_f32_e32 v152, v152
	v_rcp_f32_e32 v153, v153
	v_and_b32_e32 v163, 0xffff0000, v165
	v_pk_mul_f32 v[24:25], v[24:25], v[144:145]
	v_pk_mul_f32 v[20:21], v[20:21], v[148:149]
	v_pk_mul_f32 v[150:151], v[152:153], v[150:151]
	v_max_f32_e32 v152, v163, v163
	v_max_f32_e32 v152, 0xda24260, v152
	v_rcp_f32_e32 v155, v152
	v_pk_mul_f32 v[26:27], v[26:27], v[150:151]
	v_pk_mul_f32 v[146:147], v[154:155], v[146:147]
	s_nop 0
	v_pk_mul_f32 v[22:23], v[22:23], v[146:147]
.LBB0_565:
	v_lshlrev_b64 v[144:145], 11, v[2:3]
	s_mov_b64 s[24:25], 0x50000
	v_lshl_add_u64 v[148:149], v[144:145], 0, s[24:25]
	v_lshl_add_u64 v[144:145], s[22:23], 0, v[148:149]
	v_lshl_add_u64 v[146:147], v[144:145], 0, v[0:1]
	v_lshl_add_u64 v[144:145], s[2:3], 0, v[148:149]
	s_and_b64 vcc, exec, s[6:7]
	v_lshl_add_u64 v[144:145], v[144:145], 0, v[0:1]
	s_mov_b64 s[24:25], -1
	v_add_u32_e32 v199, 0x50000, v198
	global_load_dwordx4 v[200:203], v199, s[22:23]
	global_load_dwordx4 v[204:207], v199, s[20:21]
	global_load_dwordx4 v[208:211], v199, s[22:23] offset:256
	global_load_dwordx4 v[212:215], v199, s[20:21] offset:256
	v_add_u32_e32 v199, 0x58000, v198
	global_load_dwordx4 v[216:219], v199, s[22:23]
	global_load_dwordx4 v[220:223], v199, s[20:21]
	global_load_dwordx4 v[224:227], v199, s[22:23] offset:256
	global_load_dwordx4 v[228:231], v199, s[20:21] offset:256
	s_waitcnt vmcnt(0)
	s_nop 1
	ds_bpermute_b32 v162, v244, v200
	ds_bpermute_b32 v163, v244, v201
	ds_bpermute_b32 v164, v244, v202
	ds_bpermute_b32 v165, v244, v203
	s_waitcnt lgkmcnt(0)
	v_lshlrev_b32_e32 v156, 16, v162
	v_and_b32_e32 v157, 0xffff0000, v162
	v_lshlrev_b32_e32 v152, 16, v163
	v_and_b32_e32 v153, 0xffff0000, v163
	v_lshlrev_b32_e32 v154, 16, v164
	v_and_b32_e32 v155, 0xffff0000, v164
	v_lshlrev_b32_e32 v150, 16, v165
	v_and_b32_e32 v151, 0xffff0000, v165
	s_cbranch_vccnz .LBB0_567
	v_pk_mul_f32 v[164:165], v[50:51], v[152:153]
	v_pk_mul_f32 v[162:163], v[48:49], v[156:157]
	v_pk_mul_f32 v[192:193], v[46:47], v[150:151]
	v_pk_mul_f32 v[194:195], v[44:45], v[154:155]
	v_cvt_pk_bf16_f32 v162, v162, v163
	v_cvt_pk_bf16_f32 v163, v164, v165
	v_cvt_pk_bf16_f32 v164, v194, v195
	v_cvt_pk_bf16_f32 v165, v192, v193
	s_mov_b64 s[24:25], 0
	global_store_dwordx4 v[144:145], v[162:165], off
.LBB0_567:
	v_lshl_add_u64 v[148:149], s[20:21], 0, v[148:149]
	s_andn2_b64 vcc, exec, s[24:25]
	v_lshl_add_u64 v[148:149], v[148:149], 0, v[0:1]
	s_cbranch_vccnz .LBB0_569
	s_nop 1
	ds_bpermute_b32 v162, v244, v204
	ds_bpermute_b32 v163, v244, v205
	ds_bpermute_b32 v164, v244, v206
	ds_bpermute_b32 v165, v244, v207
	s_waitcnt lgkmcnt(0)
	v_lshlrev_b32_e32 v193, 16, v163
	v_and_b32_e32 v194, 0xffff0000, v163
	v_lshlrev_b32_e32 v163, 16, v164
	v_max_f32_e32 v163, v163, v163
	v_lshlrev_b32_e32 v182, 16, v162
	v_and_b32_e32 v192, 0xffff0000, v162
	v_max_f32_e32 v163, 0xda24260, v163
	v_and_b32_e32 v195, 0xffff0000, v164
	v_max_f32_e32 v162, v182, v182
	v_rcp_f32_e32 v164, v163
	v_max_f32_e32 v163, v192, v192
	v_max_f32_e32 v162, 0xda24260, v162
	v_max_f32_e32 v163, 0xda24260, v163
	v_rcp_f32_e32 v162, v162
	v_rcp_f32_e32 v163, v163
	v_lshlrev_b32_e32 v196, 16, v165
	v_and_b32_e32 v197, 0xffff0000, v165
	v_pk_mul_f32 v[156:157], v[162:163], v[156:157]
	v_max_f32_e32 v162, v195, v195
	v_max_f32_e32 v162, 0xda24260, v162
	v_rcp_f32_e32 v165, v162
	v_max_f32_e32 v163, v196, v196
	v_max_f32_e32 v163, 0xda24260, v163
	v_max_f32_e32 v162, v193, v193
	v_pk_mul_f32 v[154:155], v[164:165], v[154:155]
	v_rcp_f32_e32 v164, v163
	v_max_f32_e32 v163, v194, v194
	v_max_f32_e32 v162, 0xda24260, v162
	v_max_f32_e32 v163, 0xda24260, v163
	v_rcp_f32_e32 v162, v162
	v_rcp_f32_e32 v163, v163
	v_pk_mul_f32 v[48:49], v[48:49], v[156:157]
	v_pk_mul_f32 v[44:45], v[44:45], v[154:155]
	v_pk_mul_f32 v[152:153], v[162:163], v[152:153]
	v_max_f32_e32 v162, v197, v197
	v_max_f32_e32 v162, 0xda24260, v162
	v_rcp_f32_e32 v165, v162
	v_pk_mul_f32 v[50:51], v[50:51], v[152:153]
	v_pk_mul_f32 v[150:151], v[164:165], v[150:151]
	s_nop 0
	v_pk_mul_f32 v[46:47], v[46:47], v[150:151]
; #define GAS __attribute__((address_space(1)))
; __device__ __forceinline__ unsigned cvt_pk_bf16(float lo, float hi) { f32x2 v = {lo, hi}; bf16x2_t b = __builtin_convertvector(v, bf16x2_t); return __builtin_bit_cast(unsigned, b); }
; __device__ __forceinline__ float bf_lo(unsigned u) { return __uint_as_float(u << 16); }
; __device__ __forceinline__ float bf_hi(unsigned u) { return __uint_as_float(u & 0xffff0000u); }
;     __device__ __forceinline__ void operator()(f32x4 (&acc)[2][2][4][2], const Unit& u, int wr, int wc, int fr, int fq) const {
;         const int br = u.pm >> 7, pm = u.pm & 127, pn = u.pn & 3;
;         const int row0 = pm * BM + wr * 64 + fr; const int col0 = pn * BM + wc * 32 + 8 * fq;
; #pragma unroll
;         for (int ai = 0; ai < 2; ++ai)
; #pragma unroll
;             for (int m = 0; m < 4; ++m) { const int row = row0 + ai * HALF + m * 16; const GAS bf16_t* gp = ((br < 2) ? g01 + (size_t)br * MROWS * 1024 : g2) + (size_t)row * 1024 + col0; const GAS bf16_t* gn = ((br == 0) ? g01 + (size_t)MROWS * 1024 : g2) + (size_t)row * 1024 + col0; GAS bf16_t* mp = Mg + (size_t)row * 1024 + col0;
; #pragma unroll
;                 for (int bj = 0; bj < 2; ++bj) { const u32x4 g = *(const GAS u32x4*)(gp + bj * HALF);
;                     f32x4 s0 = {bf_lo(g.x), bf_hi(g.x), bf_lo(g.y), bf_hi(g.y)}, s1 = {bf_lo(g.z), bf_hi(g.z), bf_lo(g.w), bf_hi(g.w)};
;                     if (br < 2) { const u32x4 h = *(const GAS u32x4*)(gn + bj * HALF);
;                         const f32x4 d0 = {bf_lo(h.x), bf_hi(h.x), bf_lo(h.y), bf_hi(h.y)}, d1 = {bf_lo(h.z), bf_hi(h.z), bf_lo(h.w), bf_hi(h.w)};
; #pragma unroll
;                         for (int e = 0; e < 4; ++e) { s0[e] *= __builtin_amdgcn_rcpf(fmaxf(d0[e], 1e-30f)); s1[e] *= __builtin_amdgcn_rcpf(fmaxf(d1[e], 1e-30f)); }
;                         acc[ai][bj][m][0] *= s0; acc[ai][bj][m][1] *= s1;
;                     } else { const f32x4 v0 = acc[ai][bj][m][0] * s0, v1 = acc[ai][bj][m][1] * s1;
;                         u32x4 w; w.x = cvt_pk_bf16(v0[0], v0[1]); w.y = cvt_pk_bf16(v0[2], v0[3]); w.z = cvt_pk_bf16(v1[0], v1[1]); w.w = cvt_pk_bf16(v1[2], v1[3]);
;                         *(GAS u32x4*)(mp + bj * HALF) = w; } } }
.LBB0_569:
	s_and_b64 vcc, exec, s[6:7]
	s_mov_b64 s[24:25], -1
	s_nop 1
	ds_bpermute_b32 v162, v244, v208
	ds_bpermute_b32 v163, v244, v209
	ds_bpermute_b32 v164, v244, v210
	ds_bpermute_b32 v165, v244, v211
	s_waitcnt lgkmcnt(0)
	v_lshlrev_b32_e32 v154, 16, v162
	v_and_b32_e32 v155, 0xffff0000, v162
	v_lshlrev_b32_e32 v150, 16, v163
	v_and_b32_e32 v151, 0xffff0000, v163
	v_lshlrev_b32_e32 v152, 16, v164
	v_and_b32_e32 v153, 0xffff0000, v164
	v_lshlrev_b32_e32 v146, 16, v165
	v_and_b32_e32 v147, 0xffff0000, v165
	s_cbranch_vccnz .LBB0_571
	v_pk_mul_f32 v[156:157], v[18:19], v[150:151]
	v_pk_mul_f32 v[162:163], v[16:17], v[154:155]
	v_pk_mul_f32 v[192:193], v[14:15], v[146:147]
	v_pk_mul_f32 v[164:165], v[12:13], v[152:153]
	v_cvt_pk_bf16_f32 v162, v162, v163
	v_cvt_pk_bf16_f32 v163, v156, v157
	v_cvt_pk_bf16_f32 v164, v164, v165
	v_cvt_pk_bf16_f32 v165, v192, v193
	s_mov_b64 s[24:25], 0
	global_store_dwordx4 v[144:145], v[162:165], off offset:256
.LBB0_571:
	s_andn2_b64 vcc, exec, s[24:25]
	s_cbranch_vccnz .LBB0_573
	s_nop 1
	ds_bpermute_b32 v162, v244, v212
	ds_bpermute_b32 v163, v244, v213
	ds_bpermute_b32 v164, v244, v214
	ds_bpermute_b32 v165, v244, v215
	s_waitcnt lgkmcnt(0)
	v_lshlrev_b32_e32 v148, 16, v164
	v_and_b32_e32 v149, 0xffff0000, v164
	v_max_f32_e32 v148, v148, v148
	v_max_f32_e32 v149, v149, v149
	v_lshlrev_b32_e32 v144, 16, v162
	v_and_b32_e32 v145, 0xffff0000, v162
	v_max_f32_e32 v148, 0xda24260, v148
	v_max_f32_e32 v149, 0xda24260, v149
	v_max_f32_e32 v144, v144, v144
	v_rcp_f32_e32 v148, v148
	v_max_f32_e32 v145, v145, v145
	v_rcp_f32_e32 v149, v149
	v_max_f32_e32 v144, 0xda24260, v144
	v_max_f32_e32 v145, 0xda24260, v145
	v_rcp_f32_e32 v144, v144
	v_rcp_f32_e32 v145, v145
	v_lshlrev_b32_e32 v162, 16, v165
	v_pk_mul_f32 v[148:149], v[148:149], v[152:153]
	v_max_f32_e32 v153, v162, v162
	v_lshlrev_b32_e32 v156, 16, v163
	v_and_b32_e32 v157, 0xffff0000, v163
	v_max_f32_e32 v153, 0xda24260, v153
	v_pk_mul_f32 v[144:145], v[144:145], v[154:155]
	v_max_f32_e32 v152, v156, v156
	v_rcp_f32_e32 v154, v153
	v_max_f32_e32 v153, v157, v157
	v_max_f32_e32 v152, 0xda24260, v152
	v_max_f32_e32 v153, 0xda24260, v153
	v_rcp_f32_e32 v152, v152
	v_rcp_f32_e32 v153, v153
	v_and_b32_e32 v163, 0xffff0000, v165
	v_pk_mul_f32 v[16:17], v[16:17], v[144:145]
	v_pk_mul_f32 v[12:13], v[12:13], v[148:149]
	v_pk_mul_f32 v[150:151], v[152:153], v[150:151]
	v_max_f32_e32 v152, v163, v163
	v_max_f32_e32 v152, 0xda24260, v152
	v_rcp_f32_e32 v155, v152
	v_pk_mul_f32 v[18:19], v[18:19], v[150:151]
	v_pk_mul_f32 v[146:147], v[154:155], v[146:147]
	s_nop 0
	v_pk_mul_f32 v[14:15], v[14:15], v[146:147]
.LBB0_573:
	v_lshlrev_b64 v[2:3], 11, v[2:3]
	s_mov_b64 s[24:25], 0x58000
	v_lshl_add_u64 v[146:147], v[2:3], 0, s[24:25]
	v_lshl_add_u64 v[2:3], s[22:23], 0, v[146:147]
	v_lshl_add_u64 v[144:145], v[2:3], 0, v[0:1]
	v_lshl_add_u64 v[2:3], s[2:3], 0, v[146:147]
	s_and_b64 vcc, exec, s[6:7]
	v_lshl_add_u64 v[2:3], v[2:3], 0, v[0:1]
	s_mov_b64 s[22:23], -1
	s_nop 1
	ds_bpermute_b32 v162, v244, v216
	ds_bpermute_b32 v163, v244, v217
	ds_bpermute_b32 v164, v244, v218
	ds_bpermute_b32 v165, v244, v219
	s_waitcnt lgkmcnt(0)
	v_lshlrev_b32_e32 v154, 16, v162
	v_and_b32_e32 v155, 0xffff0000, v162
	v_lshlrev_b32_e32 v150, 16, v163
	v_and_b32_e32 v151, 0xffff0000, v163
	v_lshlrev_b32_e32 v152, 16, v164
	v_and_b32_e32 v153, 0xffff0000, v164
	v_lshlrev_b32_e32 v148, 16, v165
	v_and_b32_e32 v149, 0xffff0000, v165
	s_cbranch_vccnz .LBB0_575
	v_pk_mul_f32 v[156:157], v[42:43], v[150:151]
	v_pk_mul_f32 v[162:163], v[40:41], v[154:155]
	v_pk_mul_f32 v[192:193], v[38:39], v[148:149]
	v_pk_mul_f32 v[164:165], v[36:37], v[152:153]
	v_cvt_pk_bf16_f32 v162, v162, v163
	v_cvt_pk_bf16_f32 v163, v156, v157
	v_cvt_pk_bf16_f32 v164, v164, v165
	v_cvt_pk_bf16_f32 v165, v192, v193
	s_mov_b64 s[22:23], 0
	global_store_dwordx4 v[2:3], v[162:165], off
.LBB0_575:
	v_lshl_add_u64 v[146:147], s[20:21], 0, v[146:147]
	s_andn2_b64 vcc, exec, s[22:23]
	v_lshl_add_u64 v[146:147], v[146:147], 0, v[0:1]
	s_cbranch_vccnz .LBB0_577
	s_nop 1
	ds_bpermute_b32 v162, v244, v220
	ds_bpermute_b32 v163, v244, v221
	ds_bpermute_b32 v164, v244, v222
	ds_bpermute_b32 v165, v244, v223
	s_waitcnt lgkmcnt(0)
	v_lshlrev_b32_e32 v0, 16, v162
	v_max_f32_e32 v0, v0, v0
	v_and_b32_e32 v157, 0xffff0000, v162
	v_lshlrev_b32_e32 v162, 16, v164
	v_max_f32_e32 v0, 0xda24260, v0
	v_rcp_f32_e32 v156, v0
	v_max_f32_e32 v0, v162, v162
	v_max_f32_e32 v0, 0xda24260, v0
	v_rcp_f32_e32 v162, v0
	v_max_f32_e32 v0, v157, v157
	v_lshlrev_b32_e32 v182, 16, v163
	v_and_b32_e32 v192, 0xffff0000, v163
	v_and_b32_e32 v163, 0xffff0000, v164
	v_max_f32_e32 v0, 0xda24260, v0
	v_rcp_f32_e32 v157, v0
	v_max_f32_e32 v0, v163, v163
	v_max_f32_e32 v0, 0xda24260, v0
	v_rcp_f32_e32 v163, v0
	v_max_f32_e32 v0, v182, v182
	v_lshlrev_b32_e32 v164, 16, v165
	v_max_f32_e32 v0, 0xda24260, v0
	v_pk_mul_f32 v[154:155], v[156:157], v[154:155]
	v_rcp_f32_e32 v156, v0
	v_max_f32_e32 v0, v164, v164
	v_max_f32_e32 v0, 0xda24260, v0
	v_pk_mul_f32 v[152:153], v[162:163], v[152:153]
	v_rcp_f32_e32 v162, v0
	v_max_f32_e32 v0, v192, v192
	v_and_b32_e32 v165, 0xffff0000, v165
	v_max_f32_e32 v0, 0xda24260, v0
	v_rcp_f32_e32 v157, v0
	v_max_f32_e32 v0, v165, v165
	v_max_f32_e32 v0, 0xda24260, v0
	v_rcp_f32_e32 v163, v0
	v_pk_mul_f32 v[150:151], v[156:157], v[150:151]
	v_pk_mul_f32 v[40:41], v[40:41], v[154:155]
	v_pk_mul_f32 v[42:43], v[42:43], v[150:151]
	v_pk_mul_f32 v[148:149], v[162:163], v[148:149]
	v_pk_mul_f32 v[36:37], v[36:37], v[152:153]
	v_pk_mul_f32 v[38:39], v[38:39], v[148:149]
.LBB0_577:
	s_and_b64 vcc, exec, s[6:7]
	s_mov_b64 s[6:7], -1
	s_nop 1
	ds_bpermute_b32 v154, v244, v224
	ds_bpermute_b32 v155, v244, v225
	ds_bpermute_b32 v156, v244, v226
	ds_bpermute_b32 v157, v244, v227
	s_waitcnt lgkmcnt(0)
	v_lshlrev_b32_e32 v152, 16, v154
	v_and_b32_e32 v153, 0xffff0000, v154
	v_lshlrev_b32_e32 v148, 16, v155
	v_and_b32_e32 v149, 0xffff0000, v155
	v_lshlrev_b32_e32 v150, 16, v156
	v_and_b32_e32 v151, 0xffff0000, v156
	v_lshlrev_b32_e32 v144, 16, v157
	v_and_b32_e32 v145, 0xffff0000, v157
	s_cbranch_vccz .LBB0_580
	s_andn2_b64 vcc, exec, s[6:7]
	s_cbranch_vccz .LBB0_581

; #define GAS __attribute__((address_space(1)))
;     __device__ __forceinline__ void operator()(f32x4 (&acc)[2][2][4][2], const Unit& u, int wr, int wc, int fr, int fq) const {
;         const int br = u.pm >> 7, pm = u.pm & 127, pn = u.pn & 3;
;         const int row0 = pm * BM + wr * 64 + fr; const int col0 = pn * BM + wc * 32 + 8 * fq;
; #pragma unroll
;         for (int ai = 0; ai < 2; ++ai)
; #pragma unroll
;             for (int m = 0; m < 4; ++m) { const int row = row0 + ai * HALF + m * 16; const GAS bf16_t* gp = ((br < 2) ? g01 + (size_t)br * MROWS * 1024 : g2) + (size_t)row * 1024 + col0; const GAS bf16_t* gn = ((br == 0) ? g01 + (size_t)MROWS * 1024 : g2) + (size_t)row * 1024 + col0; GAS bf16_t* mp = Mg + (size_t)row * 1024 + col0;
; #pragma unroll
;                 for (int bj = 0; bj < 2; ++bj) { const u32x4 g = *(const GAS u32x4*)(gp + bj * HALF);
;                     f32x4 s0 = {bf_lo(g.x), bf_hi(g.x), bf_lo(g.y), bf_hi(g.y)}, s1 = {bf_lo(g.z), bf_hi(g.z), bf_lo(g.w), bf_hi(g.w)};
;                     if (br < 2) { const u32x4 h = *(const GAS u32x4*)(gn + bj * HALF);
;                         const f32x4 d0 = {bf_lo(h.x), bf_hi(h.x), bf_lo(h.y), bf_hi(h.y)}, d1 = {bf_lo(h.z), bf_hi(h.z), bf_lo(h.w), bf_hi(h.w)};
; #pragma unroll
;                         for (int e = 0; e < 4; ++e) { s0[e] *= __builtin_amdgcn_rcpf(fmaxf(d0[e], 1e-30f)); s1[e] *= __builtin_amdgcn_rcpf(fmaxf(d1[e], 1e-30f)); }
;                         acc[ai][bj][m][0] *= s0; acc[ai][bj][m][1] *= s1;
;                     } else { const f32x4 v0 = acc[ai][bj][m][0] * s0, v1 = acc[ai][bj][m][1] * s1;
;                         u32x4 w; w.x = cvt_pk_bf16(v0[0], v0[1]); w.y = cvt_pk_bf16(v0[2], v0[3]); w.z = cvt_pk_bf16(v1[0], v1[1]); w.w = cvt_pk_bf16(v1[2], v1[3]);
;                         *(GAS u32x4*)(mp + bj * HALF) = w; } } }
; template <class Epi, class Sched, bool ALIGN_EPI = false, bool SP2 = false>
; __device__ __forceinline__ void gemm_phase(PG8_LAS unsigned char* lds, const Gemm g, const Sched& S, const Epi& E) {
;     ...
;         if (!has_next) break;
;         bool keep_ = false; if constexpr (Epi::CHAIN) keep_ = E.keep(cur);
;         if (!keep_) {
; #pragma unroll
;         for (int a = 0; a < 2; ++a)
; #pragma unroll
;             for (int b = 0; b < 2; ++b)
; #pragma unroll
;                 for (int m = 0; m < 4; ++m)
; #pragma unroll
.LBB0_581:
	s_nop 1
	ds_bpermute_b32 v154, v244, v228
	ds_bpermute_b32 v155, v244, v229
	ds_bpermute_b32 v156, v244, v230
	ds_bpermute_b32 v157, v244, v231
	s_waitcnt lgkmcnt(0)
	v_lshlrev_b32_e32 v0, 16, v154
	v_max_f32_e32 v0, v0, v0
	v_lshlrev_b32_e32 v146, 16, v156
	v_max_f32_e32 v0, 0xda24260, v0
	v_rcp_f32_e32 v2, v0
	v_max_f32_e32 v0, v146, v146
	v_and_b32_e32 v3, 0xffff0000, v154
	v_max_f32_e32 v0, 0xda24260, v0
	v_rcp_f32_e32 v146, v0
	v_max_f32_e32 v0, v3, v3
	v_and_b32_e32 v147, 0xffff0000, v156
	v_max_f32_e32 v0, 0xda24260, v0
	v_rcp_f32_e32 v3, v0
	v_max_f32_e32 v0, v147, v147
	v_max_f32_e32 v0, 0xda24260, v0
	v_rcp_f32_e32 v147, v0
	v_lshlrev_b32_e32 v154, 16, v155
	v_max_f32_e32 v0, v154, v154
	v_lshlrev_b32_e32 v156, 16, v157
	v_max_f32_e32 v0, 0xda24260, v0
	v_pk_mul_f32 v[146:147], v[146:147], v[150:151]
	v_rcp_f32_e32 v150, v0
	v_max_f32_e32 v0, v156, v156
	v_and_b32_e32 v155, 0xffff0000, v155
	v_max_f32_e32 v0, 0xda24260, v0
	v_pk_mul_f32 v[2:3], v[2:3], v[152:153]
	v_rcp_f32_e32 v152, v0
	v_max_f32_e32 v0, v155, v155
	v_and_b32_e32 v157, 0xffff0000, v157
	v_max_f32_e32 v0, 0xda24260, v0
	v_rcp_f32_e32 v151, v0
	v_max_f32_e32 v0, v157, v157
	v_max_f32_e32 v0, 0xda24260, v0
	v_rcp_f32_e32 v153, v0
	v_pk_mul_f32 v[148:149], v[150:151], v[148:149]
	v_pk_mul_f32 v[8:9], v[8:9], v[2:3]
	v_pk_mul_f32 v[10:11], v[10:11], v[148:149]
	v_pk_mul_f32 v[144:145], v[152:153], v[144:145]
	v_pk_mul_f32 v[4:5], v[4:5], v[146:147]
	v_pk_mul_f32 v[6:7], v[6:7], v[144:145]
	s_andn2_b64 vcc, exec, s[18:19]
	s_mov_b64 s[6:7], -1
	s_cbranch_vccnz .LBB0_510
